# de-serialised the WO, FF2 and MRG epilogue loads and the MRG K-loop gate hook: loads hoisted into free VGPRs, counted vmcnt instead of vmcnt(0) per load
# speedup vs baseline: 1.0140x; 1.0140x over previous
;     __device__ __forceinline__ void khook(f32x4 (&acc)[2][2][4][2], const Unit& u, int t, int wr, int wc, int fr, int fq) const {
;         const int br = t >> 4; const bf16_t* gates = (const bf16_t*)(ws + WS_GATES) + br * 1024;
;         const int row0 = u.pm * BM + wr * 64 + fr, cw = wc * 32 + 8 * fq;
; #pragma unroll
;         for (int ai = 0; ai < 2; ++ai)
; #pragma unroll
;             for (int m = 0; m < 4; ++m) { const int row = row0 + ai * HALF + m * 16;
; #pragma unroll
;                 for (int bj = 0; bj < 2; ++bj) { const int C0 = u.pn * 256 + bj * HALF + cw;
;                     const u32x4 ga = *(const u32x4*)(gates + (size_t)row * 3072 + C0), gb = *(const u32x4*)(gates + (size_t)row * 3072 + 1024 + C0);
;                     f32x4& v0 = acc[ai][bj][m][0]; f32x4& v1 = acc[ai][bj][m][1];
;                     v0[0] *= bflo(ga.x) * __builtin_amdgcn_rcpf(bflo(gb.x)); v0[1] *= bfhi(ga.x) * __builtin_amdgcn_rcpf(bfhi(gb.x)); v0[2] *= bflo(ga.y) * __builtin_amdgcn_rcpf(bflo(gb.y)); v0[3] *= bfhi(ga.y) * __builtin_amdgcn_rcpf(bfhi(gb.y));
;                     v1[0] *= bflo(ga.z) * __builtin_amdgcn_rcpf(bflo(gb.z)); v1[1] *= bfhi(ga.z) * __builtin_amdgcn_rcpf(bfhi(gb.z)); v1[2] *= bflo(ga.w) * __builtin_amdgcn_rcpf(bflo(gb.w)); v1[3] *= bfhi(ga.w) * __builtin_amdgcn_rcpf(bfhi(gb.w)); } }
;     }
.LBB0_1103:
	s_andn2_b64 vcc, exec, s[4:5]
	s_cbranch_vccnz .LBB0_1105
	s_and_b32 s2, s63, 0x7ffffc00
	s_lshl_b32 s2, s2, 1
	s_add_u32 s36, s52, s2
	s_addc_u32 s37, s53, 0
	v_lshl_add_u64 v[128:129], s[36:37], 0, v[152:153]
	v_lshl_add_u64 v[174:175], v[128:129], 0, v[168:169]
	v_lshl_add_u64 v[204:205], s[36:37], 0, v[152:153]
	v_lshl_add_u64 v[204:205], v[204:205], 0, v[168:169]
	global_load_dwordx4 v[180:183], v[204:205], off
	global_load_dwordx4 v[184:187], v[204:205], off offset:2048
	global_load_dwordx4 v[188:191], v[204:205], off offset:256
	global_load_dwordx4 v[192:195], v[204:205], off offset:2304
	v_lshl_add_u64 v[204:205], s[36:37], 0, v[154:155]
	v_lshl_add_u64 v[204:205], v[204:205], 0, v[168:169]
	global_load_dwordx4 v[196:199], v[204:205], off
	global_load_dwordx4 v[200:203], v[204:205], off offset:2048
	global_load_dwordx4 v[216:219], v[204:205], off offset:256
	global_load_dwordx4 v[220:223], v[204:205], off offset:2304
	v_lshl_add_u64 v[204:205], s[36:37], 0, v[156:157]
	v_lshl_add_u64 v[204:205], v[204:205], 0, v[168:169]
	global_load_dwordx4 v[224:227], v[204:205], off
	global_load_dwordx4 v[228:231], v[204:205], off offset:2048
	global_load_dwordx4 v[234:237], v[204:205], off offset:256
	global_load_dwordx4 v[238:241], v[204:205], off offset:2304
	v_lshl_add_u64 v[204:205], s[36:37], 0, v[158:159]
	v_lshl_add_u64 v[204:205], v[204:205], 0, v[168:169]
	global_load_dwordx4 v[242:245], v[204:205], off
	global_load_dwordx4 v[246:249], v[204:205], off offset:2048
	s_waitcnt vmcnt(12)
	v_mov_b32_e32 v128, v180
	v_mov_b32_e32 v129, v181
	v_mov_b32_e32 v130, v182
	v_mov_b32_e32 v131, v183
	v_mov_b32_e32 v132, v184
	v_mov_b32_e32 v133, v185
	v_mov_b32_e32 v134, v186
	v_mov_b32_e32 v135, v187
	global_load_dwordx4 v[180:183], v[204:205], off offset:256
	global_load_dwordx4 v[184:187], v[204:205], off offset:2304
	v_lshlrev_b32_e32 v178, 16, v128
	v_lshlrev_b32_e32 v147, 16, v132
	v_and_b32_e32 v132, 0xffff0000, v132
	v_and_b32_e32 v179, 0xffff0000, v128
	v_lshlrev_b32_e32 v128, 16, v133
	v_rcp_f32_e32 v177, v132
	v_rcp_f32_e32 v132, v128
	v_and_b32_e32 v128, 0xffff0000, v133
	v_rcp_f32_e32 v133, v128
	v_lshlrev_b32_e32 v128, 16, v129
	v_and_b32_e32 v129, 0xffff0000, v129
	v_rcp_f32_e32 v176, v147
	v_pk_mul_f32 v[128:129], v[132:133], v[128:129]
	v_lshlrev_b32_e32 v132, 16, v130
	v_pk_mul_f32 v[126:127], v[126:127], v[128:129]
	v_lshlrev_b32_e32 v128, 16, v134
	v_and_b32_e32 v129, 0xffff0000, v134
	v_rcp_f32_e32 v128, v128
	v_rcp_f32_e32 v129, v129
	v_and_b32_e32 v133, 0xffff0000, v130
	v_lshlrev_b32_e32 v130, 16, v131
	v_and_b32_e32 v131, 0xffff0000, v131
	v_pk_mul_f32 v[128:129], v[128:129], v[132:133]
	v_pk_mul_f32 v[176:177], v[176:177], v[178:179]
	v_pk_mul_f32 v[120:121], v[120:121], v[128:129]
	v_lshlrev_b32_e32 v128, 16, v135
	v_and_b32_e32 v129, 0xffff0000, v135
	v_rcp_f32_e32 v128, v128
	v_rcp_f32_e32 v129, v129
	v_pk_mul_f32 v[124:125], v[124:125], v[176:177]
	v_pk_mul_f32 v[128:129], v[128:129], v[130:131]
	s_nop 0
	v_pk_mul_f32 v[122:123], v[122:123], v[128:129]
	s_waitcnt vmcnt(12)
	v_mov_b32_e32 v128, v188
	v_mov_b32_e32 v129, v189
	v_mov_b32_e32 v130, v190
	v_mov_b32_e32 v131, v191
	v_mov_b32_e32 v132, v192
	v_mov_b32_e32 v133, v193
	v_mov_b32_e32 v134, v194
	v_mov_b32_e32 v135, v195
	v_lshl_add_u64 v[204:205], s[36:37], 0, v[160:161]
	v_lshl_add_u64 v[204:205], v[204:205], 0, v[168:169]
	global_load_dwordx4 v[188:191], v[204:205], off
	global_load_dwordx4 v[192:195], v[204:205], off offset:2048
	v_lshlrev_b32_e32 v176, 16, v128
	v_lshlrev_b32_e32 v147, 16, v132
	v_and_b32_e32 v132, 0xffff0000, v132
	v_and_b32_e32 v177, 0xffff0000, v128
	v_lshlrev_b32_e32 v128, 16, v133
	v_rcp_f32_e32 v175, v132
	v_rcp_f32_e32 v132, v128
	v_and_b32_e32 v128, 0xffff0000, v133
	v_rcp_f32_e32 v133, v128
	v_lshlrev_b32_e32 v128, 16, v129
	v_and_b32_e32 v129, 0xffff0000, v129
	v_rcp_f32_e32 v174, v147
	v_pk_mul_f32 v[128:129], v[132:133], v[128:129]
	v_lshlrev_b32_e32 v132, 16, v130
	v_pk_mul_f32 v[118:119], v[118:119], v[128:129]
	v_lshlrev_b32_e32 v128, 16, v134
	v_and_b32_e32 v129, 0xffff0000, v134
	v_rcp_f32_e32 v128, v128
	v_rcp_f32_e32 v129, v129
	v_and_b32_e32 v133, 0xffff0000, v130
	v_lshlrev_b32_e32 v130, 16, v131
	v_and_b32_e32 v131, 0xffff0000, v131
	v_pk_mul_f32 v[128:129], v[128:129], v[132:133]
	v_pk_mul_f32 v[174:175], v[174:175], v[176:177]
	v_pk_mul_f32 v[112:113], v[112:113], v[128:129]
	v_lshlrev_b32_e32 v128, 16, v135
	v_and_b32_e32 v129, 0xffff0000, v135
	v_rcp_f32_e32 v128, v128
	v_rcp_f32_e32 v129, v129
	v_pk_mul_f32 v[116:117], v[116:117], v[174:175]
	v_pk_mul_f32 v[128:129], v[128:129], v[130:131]
	s_nop 0
	v_pk_mul_f32 v[114:115], v[114:115], v[128:129]
	v_lshl_add_u64 v[128:129], s[36:37], 0, v[154:155]
	v_lshl_add_u64 v[174:175], v[128:129], 0, v[168:169]
	s_waitcnt vmcnt(12)
	v_mov_b32_e32 v128, v196
	v_mov_b32_e32 v129, v197
	v_mov_b32_e32 v130, v198
	v_mov_b32_e32 v131, v199
	v_mov_b32_e32 v132, v200
	v_mov_b32_e32 v133, v201
	v_mov_b32_e32 v134, v202
	v_mov_b32_e32 v135, v203
	global_load_dwordx4 v[196:199], v[204:205], off offset:256
	global_load_dwordx4 v[200:203], v[204:205], off offset:2304
	v_lshlrev_b32_e32 v178, 16, v128
	v_lshlrev_b32_e32 v147, 16, v132
	v_and_b32_e32 v132, 0xffff0000, v132
	v_and_b32_e32 v179, 0xffff0000, v128
	v_lshlrev_b32_e32 v128, 16, v133
	v_rcp_f32_e32 v177, v132
	v_rcp_f32_e32 v132, v128
	v_and_b32_e32 v128, 0xffff0000, v133
	v_rcp_f32_e32 v133, v128
	v_lshlrev_b32_e32 v128, 16, v129
	v_and_b32_e32 v129, 0xffff0000, v129
	v_rcp_f32_e32 v176, v147
	v_pk_mul_f32 v[128:129], v[132:133], v[128:129]
	v_lshlrev_b32_e32 v132, 16, v130
	v_pk_mul_f32 v[110:111], v[110:111], v[128:129]
	v_lshlrev_b32_e32 v128, 16, v134
	v_and_b32_e32 v129, 0xffff0000, v134
	v_rcp_f32_e32 v128, v128
	v_rcp_f32_e32 v129, v129
	v_and_b32_e32 v133, 0xffff0000, v130
	v_lshlrev_b32_e32 v130, 16, v131
	v_and_b32_e32 v131, 0xffff0000, v131
	v_pk_mul_f32 v[128:129], v[128:129], v[132:133]
	v_pk_mul_f32 v[176:177], v[176:177], v[178:179]
	v_pk_mul_f32 v[104:105], v[104:105], v[128:129]
	v_lshlrev_b32_e32 v128, 16, v135
	v_and_b32_e32 v129, 0xffff0000, v135
	v_rcp_f32_e32 v128, v128
	v_rcp_f32_e32 v129, v129
	v_pk_mul_f32 v[108:109], v[108:109], v[176:177]
	v_pk_mul_f32 v[128:129], v[128:129], v[130:131]
	s_nop 0
	v_pk_mul_f32 v[106:107], v[106:107], v[128:129]
	s_waitcnt vmcnt(12)
;     __device__ __forceinline__ void khook(f32x4 (&acc)[2][2][4][2], const Unit& u, int t, int wr, int wc, int fr, int fq) const {
;         const int br = t >> 4; const bf16_t* gates = (const bf16_t*)(ws + WS_GATES) + br * 1024;
;         const int row0 = u.pm * BM + wr * 64 + fr, cw = wc * 32 + 8 * fq;
; #pragma unroll
;         for (int ai = 0; ai < 2; ++ai)
; #pragma unroll
;             for (int m = 0; m < 4; ++m) { const int row = row0 + ai * HALF + m * 16;
; #pragma unroll
;                 for (int bj = 0; bj < 2; ++bj) { const int C0 = u.pn * 256 + bj * HALF + cw;
;                     const u32x4 ga = *(const u32x4*)(gates + (size_t)row * 3072 + C0), gb = *(const u32x4*)(gates + (size_t)row * 3072 + 1024 + C0);
;                     f32x4& v0 = acc[ai][bj][m][0]; f32x4& v1 = acc[ai][bj][m][1];
;                     v0[0] *= bflo(ga.x) * __builtin_amdgcn_rcpf(bflo(gb.x)); v0[1] *= bfhi(ga.x) * __builtin_amdgcn_rcpf(bfhi(gb.x)); v0[2] *= bflo(ga.y) * __builtin_amdgcn_rcpf(bflo(gb.y)); v0[3] *= bfhi(ga.y) * __builtin_amdgcn_rcpf(bfhi(gb.y));
;                     v1[0] *= bflo(ga.z) * __builtin_amdgcn_rcpf(bflo(gb.z)); v1[1] *= bfhi(ga.z) * __builtin_amdgcn_rcpf(bfhi(gb.z)); v1[2] *= bflo(ga.w) * __builtin_amdgcn_rcpf(bflo(gb.w)); v1[3] *= bfhi(ga.w) * __builtin_amdgcn_rcpf(bfhi(gb.w)); } }
;     }
	v_mov_b32_e32 v128, v216
	v_mov_b32_e32 v129, v217
	v_mov_b32_e32 v130, v218
	v_mov_b32_e32 v131, v219
	v_mov_b32_e32 v132, v220
	v_mov_b32_e32 v133, v221
	v_mov_b32_e32 v134, v222
	v_mov_b32_e32 v135, v223
	v_lshl_add_u64 v[204:205], s[36:37], 0, v[162:163]
	v_lshl_add_u64 v[204:205], v[204:205], 0, v[168:169]
	global_load_dwordx4 v[216:219], v[204:205], off
	global_load_dwordx4 v[220:223], v[204:205], off offset:2048
	v_lshlrev_b32_e32 v176, 16, v128
	v_lshlrev_b32_e32 v147, 16, v132
	v_and_b32_e32 v132, 0xffff0000, v132
	v_and_b32_e32 v177, 0xffff0000, v128
	v_lshlrev_b32_e32 v128, 16, v133
	v_rcp_f32_e32 v175, v132
	v_rcp_f32_e32 v132, v128
	v_and_b32_e32 v128, 0xffff0000, v133
	v_rcp_f32_e32 v133, v128
	v_lshlrev_b32_e32 v128, 16, v129
	v_and_b32_e32 v129, 0xffff0000, v129
	v_rcp_f32_e32 v174, v147
	v_pk_mul_f32 v[128:129], v[132:133], v[128:129]
	v_lshlrev_b32_e32 v132, 16, v130
	v_pk_mul_f32 v[102:103], v[102:103], v[128:129]
	v_lshlrev_b32_e32 v128, 16, v134
	v_and_b32_e32 v129, 0xffff0000, v134
	v_rcp_f32_e32 v128, v128
	v_rcp_f32_e32 v129, v129
	v_and_b32_e32 v133, 0xffff0000, v130
	v_lshlrev_b32_e32 v130, 16, v131
	v_and_b32_e32 v131, 0xffff0000, v131
	v_pk_mul_f32 v[128:129], v[128:129], v[132:133]
	v_pk_mul_f32 v[174:175], v[174:175], v[176:177]
	v_pk_mul_f32 v[96:97], v[96:97], v[128:129]
	v_lshlrev_b32_e32 v128, 16, v135
	v_and_b32_e32 v129, 0xffff0000, v135
	v_rcp_f32_e32 v128, v128
	v_rcp_f32_e32 v129, v129
	v_pk_mul_f32 v[100:101], v[100:101], v[174:175]
	v_pk_mul_f32 v[128:129], v[128:129], v[130:131]
	s_nop 0
	v_pk_mul_f32 v[98:99], v[98:99], v[128:129]
	v_lshl_add_u64 v[128:129], s[36:37], 0, v[156:157]
	v_lshl_add_u64 v[132:133], v[128:129], 0, v[168:169]
	s_waitcnt vmcnt(12)
	v_mov_b32_e32 v128, v224
	v_mov_b32_e32 v129, v225
	v_mov_b32_e32 v130, v226
	v_mov_b32_e32 v131, v227
	v_mov_b32_e32 v174, v228
	v_mov_b32_e32 v175, v229
	v_mov_b32_e32 v176, v230
	v_mov_b32_e32 v177, v231
	global_load_dwordx4 v[224:227], v[204:205], off offset:256
	global_load_dwordx4 v[228:231], v[204:205], off offset:2304
	v_lshlrev_b32_e32 v178, 16, v128
	v_lshlrev_b32_e32 v134, 16, v174
	v_and_b32_e32 v135, 0xffff0000, v174
	v_rcp_f32_e32 v134, v134
	v_rcp_f32_e32 v135, v135
	v_and_b32_e32 v179, 0xffff0000, v128
	v_lshlrev_b32_e32 v128, 16, v175
	v_pk_mul_f32 v[134:135], v[134:135], v[178:179]
	s_nop 0
	v_pk_mul_f32 v[92:93], v[92:93], v[134:135]
	v_rcp_f32_e32 v134, v128
	v_and_b32_e32 v128, 0xffff0000, v175
	v_rcp_f32_e32 v135, v128
	v_lshlrev_b32_e32 v128, 16, v129
	v_and_b32_e32 v129, 0xffff0000, v129
	v_pk_mul_f32 v[128:129], v[134:135], v[128:129]
	s_nop 0
	v_pk_mul_f32 v[94:95], v[94:95], v[128:129]
	v_lshlrev_b32_e32 v128, 16, v176
	v_and_b32_e32 v129, 0xffff0000, v176
	v_rcp_f32_e32 v128, v128
	v_rcp_f32_e32 v129, v129
	v_lshlrev_b32_e32 v134, 16, v130
	v_and_b32_e32 v135, 0xffff0000, v130
	v_lshlrev_b32_e32 v130, 16, v131
	v_pk_mul_f32 v[128:129], v[128:129], v[134:135]
	v_and_b32_e32 v131, 0xffff0000, v131
	v_pk_mul_f32 v[88:89], v[88:89], v[128:129]
	v_lshlrev_b32_e32 v128, 16, v177
	v_and_b32_e32 v129, 0xffff0000, v177
	v_rcp_f32_e32 v128, v128
	v_rcp_f32_e32 v129, v129
	s_nop 0
	v_pk_mul_f32 v[128:129], v[128:129], v[130:131]
	s_nop 0
	v_pk_mul_f32 v[90:91], v[90:91], v[128:129]
	s_nop 0
	s_waitcnt vmcnt(12)
	v_mov_b32_e32 v128, v234
	v_mov_b32_e32 v129, v235
	v_mov_b32_e32 v130, v236
	v_mov_b32_e32 v131, v237
	v_mov_b32_e32 v132, v238
	v_mov_b32_e32 v133, v239
	v_mov_b32_e32 v134, v240
	v_mov_b32_e32 v135, v241
	v_lshl_add_u64 v[204:205], s[36:37], 0, v[164:165]
	v_lshl_add_u64 v[204:205], v[204:205], 0, v[168:169]
	global_load_dwordx4 v[234:237], v[204:205], off
	global_load_dwordx4 v[238:241], v[204:205], off offset:2048
	v_lshlrev_b32_e32 v176, 16, v128
	v_lshlrev_b32_e32 v147, 16, v132
	v_and_b32_e32 v132, 0xffff0000, v132
	v_and_b32_e32 v177, 0xffff0000, v128
	v_lshlrev_b32_e32 v128, 16, v133
	v_rcp_f32_e32 v175, v132
	v_rcp_f32_e32 v132, v128
	v_and_b32_e32 v128, 0xffff0000, v133
	v_rcp_f32_e32 v133, v128
	v_lshlrev_b32_e32 v128, 16, v129
	v_and_b32_e32 v129, 0xffff0000, v129
	v_rcp_f32_e32 v174, v147
	v_pk_mul_f32 v[128:129], v[132:133], v[128:129]
	v_lshlrev_b32_e32 v132, 16, v130
	v_pk_mul_f32 v[86:87], v[86:87], v[128:129]
	v_lshlrev_b32_e32 v128, 16, v134
	v_and_b32_e32 v129, 0xffff0000, v134
	v_rcp_f32_e32 v128, v128
	v_rcp_f32_e32 v129, v129
	v_and_b32_e32 v133, 0xffff0000, v130
	v_lshlrev_b32_e32 v130, 16, v131
	v_and_b32_e32 v131, 0xffff0000, v131
	v_pk_mul_f32 v[128:129], v[128:129], v[132:133]
	v_pk_mul_f32 v[174:175], v[174:175], v[176:177]
	v_pk_mul_f32 v[80:81], v[80:81], v[128:129]
	v_lshlrev_b32_e32 v128, 16, v135
	v_and_b32_e32 v129, 0xffff0000, v135
	v_rcp_f32_e32 v128, v128
	v_rcp_f32_e32 v129, v129
	v_pk_mul_f32 v[84:85], v[84:85], v[174:175]
	v_pk_mul_f32 v[128:129], v[128:129], v[130:131]
	s_nop 0
	v_pk_mul_f32 v[82:83], v[82:83], v[128:129]
	v_lshl_add_u64 v[128:129], s[36:37], 0, v[158:159]
	v_lshl_add_u64 v[132:133], v[128:129], 0, v[168:169]
	s_waitcnt vmcnt(12)
;     __device__ __forceinline__ void khook(f32x4 (&acc)[2][2][4][2], const Unit& u, int t, int wr, int wc, int fr, int fq) const {
;         const int br = t >> 4; const bf16_t* gates = (const bf16_t*)(ws + WS_GATES) + br * 1024;
;         const int row0 = u.pm * BM + wr * 64 + fr, cw = wc * 32 + 8 * fq;
; #pragma unroll
;         for (int ai = 0; ai < 2; ++ai)
; #pragma unroll
;             for (int m = 0; m < 4; ++m) { const int row = row0 + ai * HALF + m * 16;
; #pragma unroll
;                 for (int bj = 0; bj < 2; ++bj) { const int C0 = u.pn * 256 + bj * HALF + cw;
;                     const u32x4 ga = *(const u32x4*)(gates + (size_t)row * 3072 + C0), gb = *(const u32x4*)(gates + (size_t)row * 3072 + 1024 + C0);
;                     f32x4& v0 = acc[ai][bj][m][0]; f32x4& v1 = acc[ai][bj][m][1];
;                     v0[0] *= bflo(ga.x) * __builtin_amdgcn_rcpf(bflo(gb.x)); v0[1] *= bfhi(ga.x) * __builtin_amdgcn_rcpf(bfhi(gb.x)); v0[2] *= bflo(ga.y) * __builtin_amdgcn_rcpf(bflo(gb.y)); v0[3] *= bfhi(ga.y) * __builtin_amdgcn_rcpf(bfhi(gb.y));
;                     v1[0] *= bflo(ga.z) * __builtin_amdgcn_rcpf(bflo(gb.z)); v1[1] *= bfhi(ga.z) * __builtin_amdgcn_rcpf(bfhi(gb.z)); v1[2] *= bflo(ga.w) * __builtin_amdgcn_rcpf(bflo(gb.w)); v1[3] *= bfhi(ga.w) * __builtin_amdgcn_rcpf(bfhi(gb.w)); } }
;     }
	v_mov_b32_e32 v128, v242
	v_mov_b32_e32 v129, v243
	v_mov_b32_e32 v130, v244
	v_mov_b32_e32 v131, v245
	v_mov_b32_e32 v174, v246
	v_mov_b32_e32 v175, v247
	v_mov_b32_e32 v176, v248
	v_mov_b32_e32 v177, v249
	global_load_dwordx4 v[242:245], v[204:205], off offset:256
	global_load_dwordx4 v[246:249], v[204:205], off offset:2304
	v_lshlrev_b32_e32 v178, 16, v128
	v_lshlrev_b32_e32 v134, 16, v174
	v_and_b32_e32 v135, 0xffff0000, v174
	v_rcp_f32_e32 v134, v134
	v_rcp_f32_e32 v135, v135
	v_and_b32_e32 v179, 0xffff0000, v128
	v_lshlrev_b32_e32 v128, 16, v175
	v_pk_mul_f32 v[134:135], v[134:135], v[178:179]
	s_nop 0
	v_pk_mul_f32 v[76:77], v[76:77], v[134:135]
	v_rcp_f32_e32 v134, v128
	v_and_b32_e32 v128, 0xffff0000, v175
	v_rcp_f32_e32 v135, v128
	v_lshlrev_b32_e32 v128, 16, v129
	v_and_b32_e32 v129, 0xffff0000, v129
	v_pk_mul_f32 v[128:129], v[134:135], v[128:129]
	s_nop 0
	v_pk_mul_f32 v[78:79], v[78:79], v[128:129]
	v_lshlrev_b32_e32 v128, 16, v176
	v_and_b32_e32 v129, 0xffff0000, v176
	v_rcp_f32_e32 v128, v128
	v_rcp_f32_e32 v129, v129
	v_lshlrev_b32_e32 v134, 16, v130
	v_and_b32_e32 v135, 0xffff0000, v130
	v_lshlrev_b32_e32 v130, 16, v131
	v_pk_mul_f32 v[128:129], v[128:129], v[134:135]
	v_and_b32_e32 v131, 0xffff0000, v131
	v_pk_mul_f32 v[72:73], v[72:73], v[128:129]
	v_lshlrev_b32_e32 v128, 16, v177
	v_and_b32_e32 v129, 0xffff0000, v177
	v_rcp_f32_e32 v128, v128
	v_rcp_f32_e32 v129, v129
	s_nop 0
	v_pk_mul_f32 v[128:129], v[128:129], v[130:131]
	s_nop 0
	v_pk_mul_f32 v[74:75], v[74:75], v[128:129]
	s_nop 0
	s_waitcnt vmcnt(12)
	v_mov_b32_e32 v128, v180
	v_mov_b32_e32 v129, v181
	v_mov_b32_e32 v130, v182
	v_mov_b32_e32 v131, v183
	v_mov_b32_e32 v132, v184
	v_mov_b32_e32 v133, v185
	v_mov_b32_e32 v134, v186
	v_mov_b32_e32 v135, v187
	v_lshl_add_u64 v[204:205], s[36:37], 0, v[166:167]
	v_lshl_add_u64 v[204:205], v[204:205], 0, v[168:169]
	global_load_dwordx4 v[180:183], v[204:205], off
	global_load_dwordx4 v[184:187], v[204:205], off offset:2048
	v_lshlrev_b32_e32 v176, 16, v128
	v_lshlrev_b32_e32 v147, 16, v132
	v_and_b32_e32 v132, 0xffff0000, v132
	v_and_b32_e32 v177, 0xffff0000, v128
	v_lshlrev_b32_e32 v128, 16, v133
	v_rcp_f32_e32 v175, v132
	v_rcp_f32_e32 v132, v128
	v_and_b32_e32 v128, 0xffff0000, v133
	v_rcp_f32_e32 v133, v128
	v_lshlrev_b32_e32 v128, 16, v129
	v_and_b32_e32 v129, 0xffff0000, v129
	v_rcp_f32_e32 v174, v147
	v_pk_mul_f32 v[128:129], v[132:133], v[128:129]
	v_lshlrev_b32_e32 v132, 16, v130
	v_pk_mul_f32 v[70:71], v[70:71], v[128:129]
	v_lshlrev_b32_e32 v128, 16, v134
	v_and_b32_e32 v129, 0xffff0000, v134
	v_rcp_f32_e32 v128, v128
	v_rcp_f32_e32 v129, v129
	v_and_b32_e32 v133, 0xffff0000, v130
	v_lshlrev_b32_e32 v130, 16, v131
	v_and_b32_e32 v131, 0xffff0000, v131
	v_pk_mul_f32 v[128:129], v[128:129], v[132:133]
	v_pk_mul_f32 v[174:175], v[174:175], v[176:177]
	v_pk_mul_f32 v[64:65], v[64:65], v[128:129]
	v_lshlrev_b32_e32 v128, 16, v135
	v_and_b32_e32 v129, 0xffff0000, v135
	v_rcp_f32_e32 v128, v128
	v_rcp_f32_e32 v129, v129
	v_pk_mul_f32 v[68:69], v[68:69], v[174:175]
	v_pk_mul_f32 v[128:129], v[128:129], v[130:131]
	s_nop 0
	v_pk_mul_f32 v[66:67], v[66:67], v[128:129]
	v_lshl_add_u64 v[128:129], s[36:37], 0, v[160:161]
	v_lshl_add_u64 v[132:133], v[128:129], 0, v[168:169]
	s_waitcnt vmcnt(12)
	v_mov_b32_e32 v128, v188
	v_mov_b32_e32 v129, v189
	v_mov_b32_e32 v130, v190
	v_mov_b32_e32 v131, v191
	v_mov_b32_e32 v174, v192
	v_mov_b32_e32 v175, v193
	v_mov_b32_e32 v176, v194
	v_mov_b32_e32 v177, v195
	global_load_dwordx4 v[188:191], v[204:205], off offset:256
	global_load_dwordx4 v[192:195], v[204:205], off offset:2304
	v_lshlrev_b32_e32 v178, 16, v128
	v_lshlrev_b32_e32 v134, 16, v174
	v_and_b32_e32 v135, 0xffff0000, v174
	v_rcp_f32_e32 v134, v134
	v_rcp_f32_e32 v135, v135
	v_and_b32_e32 v179, 0xffff0000, v128
	v_lshlrev_b32_e32 v128, 16, v175
	v_pk_mul_f32 v[134:135], v[134:135], v[178:179]
	s_nop 0
	v_pk_mul_f32 v[60:61], v[60:61], v[134:135]
	v_rcp_f32_e32 v134, v128
	v_and_b32_e32 v128, 0xffff0000, v175
	v_rcp_f32_e32 v135, v128
	v_lshlrev_b32_e32 v128, 16, v129
	v_and_b32_e32 v129, 0xffff0000, v129
	v_pk_mul_f32 v[128:129], v[134:135], v[128:129]
	s_nop 0
	v_pk_mul_f32 v[62:63], v[62:63], v[128:129]
	v_lshlrev_b32_e32 v128, 16, v176
	v_and_b32_e32 v129, 0xffff0000, v176
	v_rcp_f32_e32 v128, v128
	v_rcp_f32_e32 v129, v129
	v_lshlrev_b32_e32 v134, 16, v130
	v_and_b32_e32 v135, 0xffff0000, v130
	v_lshlrev_b32_e32 v130, 16, v131
	v_pk_mul_f32 v[128:129], v[128:129], v[134:135]
	v_and_b32_e32 v131, 0xffff0000, v131
	v_pk_mul_f32 v[56:57], v[56:57], v[128:129]
	v_lshlrev_b32_e32 v128, 16, v177
	v_and_b32_e32 v129, 0xffff0000, v177
	v_rcp_f32_e32 v128, v128
	v_rcp_f32_e32 v129, v129
	s_nop 0
	v_pk_mul_f32 v[128:129], v[128:129], v[130:131]
	s_nop 0
	v_pk_mul_f32 v[58:59], v[58:59], v[128:129]
	s_nop 0
	s_waitcnt vmcnt(12)
	v_mov_b32_e32 v128, v196
	v_mov_b32_e32 v129, v197
	v_mov_b32_e32 v130, v198
	v_mov_b32_e32 v131, v199
	v_mov_b32_e32 v132, v200
	v_mov_b32_e32 v133, v201
	v_mov_b32_e32 v134, v202
	v_mov_b32_e32 v135, v203
	v_lshlrev_b32_e32 v176, 16, v128
	v_lshlrev_b32_e32 v147, 16, v132
	v_and_b32_e32 v132, 0xffff0000, v132
	v_and_b32_e32 v177, 0xffff0000, v128
	v_lshlrev_b32_e32 v128, 16, v133
	v_rcp_f32_e32 v175, v132
	v_rcp_f32_e32 v132, v128
	v_and_b32_e32 v128, 0xffff0000, v133
	v_rcp_f32_e32 v133, v128
	v_lshlrev_b32_e32 v128, 16, v129
	v_and_b32_e32 v129, 0xffff0000, v129
	v_rcp_f32_e32 v174, v147
	v_pk_mul_f32 v[128:129], v[132:133], v[128:129]
	v_lshlrev_b32_e32 v132, 16, v130
	v_pk_mul_f32 v[54:55], v[54:55], v[128:129]
	v_lshlrev_b32_e32 v128, 16, v134
	v_and_b32_e32 v129, 0xffff0000, v134
	v_rcp_f32_e32 v128, v128
	v_rcp_f32_e32 v129, v129
	v_and_b32_e32 v133, 0xffff0000, v130
	v_lshlrev_b32_e32 v130, 16, v131
	v_and_b32_e32 v131, 0xffff0000, v131
	v_pk_mul_f32 v[128:129], v[128:129], v[132:133]
	v_pk_mul_f32 v[174:175], v[174:175], v[176:177]
	v_pk_mul_f32 v[48:49], v[48:49], v[128:129]
	v_lshlrev_b32_e32 v128, 16, v135
	v_and_b32_e32 v129, 0xffff0000, v135
	v_rcp_f32_e32 v128, v128
	v_rcp_f32_e32 v129, v129
	v_pk_mul_f32 v[52:53], v[52:53], v[174:175]
	v_pk_mul_f32 v[128:129], v[128:129], v[130:131]
	s_nop 0
	v_pk_mul_f32 v[50:51], v[50:51], v[128:129]
	v_lshl_add_u64 v[128:129], s[36:37], 0, v[162:163]
	v_lshl_add_u64 v[132:133], v[128:129], 0, v[168:169]
	s_waitcnt vmcnt(10)
;     __device__ __forceinline__ void khook(f32x4 (&acc)[2][2][4][2], const Unit& u, int t, int wr, int wc, int fr, int fq) const {
;         const int br = t >> 4; const bf16_t* gates = (const bf16_t*)(ws + WS_GATES) + br * 1024;
;         const int row0 = u.pm * BM + wr * 64 + fr, cw = wc * 32 + 8 * fq;
; #pragma unroll
;         for (int ai = 0; ai < 2; ++ai)
; #pragma unroll
;             for (int m = 0; m < 4; ++m) { const int row = row0 + ai * HALF + m * 16;
; #pragma unroll
;                 for (int bj = 0; bj < 2; ++bj) { const int C0 = u.pn * 256 + bj * HALF + cw;
;                     const u32x4 ga = *(const u32x4*)(gates + (size_t)row * 3072 + C0), gb = *(const u32x4*)(gates + (size_t)row * 3072 + 1024 + C0);
;                     f32x4& v0 = acc[ai][bj][m][0]; f32x4& v1 = acc[ai][bj][m][1];
;                     v0[0] *= bflo(ga.x) * __builtin_amdgcn_rcpf(bflo(gb.x)); v0[1] *= bfhi(ga.x) * __builtin_amdgcn_rcpf(bfhi(gb.x)); v0[2] *= bflo(ga.y) * __builtin_amdgcn_rcpf(bflo(gb.y)); v0[3] *= bfhi(ga.y) * __builtin_amdgcn_rcpf(bfhi(gb.y));
;                     v1[0] *= bflo(ga.z) * __builtin_amdgcn_rcpf(bflo(gb.z)); v1[1] *= bfhi(ga.z) * __builtin_amdgcn_rcpf(bfhi(gb.z)); v1[2] *= bflo(ga.w) * __builtin_amdgcn_rcpf(bflo(gb.w)); v1[3] *= bfhi(ga.w) * __builtin_amdgcn_rcpf(bfhi(gb.w)); } }
;     }
	v_mov_b32_e32 v128, v216
	v_mov_b32_e32 v129, v217
	v_mov_b32_e32 v130, v218
	v_mov_b32_e32 v131, v219
	v_mov_b32_e32 v174, v220
	v_mov_b32_e32 v175, v221
	v_mov_b32_e32 v176, v222
	v_mov_b32_e32 v177, v223
	v_lshlrev_b32_e32 v178, 16, v128
	v_lshlrev_b32_e32 v134, 16, v174
	v_and_b32_e32 v135, 0xffff0000, v174
	v_rcp_f32_e32 v134, v134
	v_rcp_f32_e32 v135, v135
	v_and_b32_e32 v179, 0xffff0000, v128
	v_lshlrev_b32_e32 v128, 16, v175
	v_pk_mul_f32 v[134:135], v[134:135], v[178:179]
	s_nop 0
	v_pk_mul_f32 v[44:45], v[44:45], v[134:135]
	v_rcp_f32_e32 v134, v128
	v_and_b32_e32 v128, 0xffff0000, v175
	v_rcp_f32_e32 v135, v128
	v_lshlrev_b32_e32 v128, 16, v129
	v_and_b32_e32 v129, 0xffff0000, v129
	v_pk_mul_f32 v[128:129], v[134:135], v[128:129]
	s_nop 0
	v_pk_mul_f32 v[46:47], v[46:47], v[128:129]
	v_lshlrev_b32_e32 v128, 16, v176
	v_and_b32_e32 v129, 0xffff0000, v176
	v_rcp_f32_e32 v128, v128
	v_rcp_f32_e32 v129, v129
	v_lshlrev_b32_e32 v134, 16, v130
	v_and_b32_e32 v135, 0xffff0000, v130
	v_lshlrev_b32_e32 v130, 16, v131
	v_pk_mul_f32 v[128:129], v[128:129], v[134:135]
	v_and_b32_e32 v131, 0xffff0000, v131
	v_pk_mul_f32 v[40:41], v[40:41], v[128:129]
	v_lshlrev_b32_e32 v128, 16, v177
	v_and_b32_e32 v129, 0xffff0000, v177
	v_rcp_f32_e32 v128, v128
	v_rcp_f32_e32 v129, v129
	s_nop 0
	v_pk_mul_f32 v[128:129], v[128:129], v[130:131]
	s_nop 0
	v_pk_mul_f32 v[42:43], v[42:43], v[128:129]
	s_nop 0
	s_waitcnt vmcnt(8)
	v_mov_b32_e32 v128, v224
	v_mov_b32_e32 v129, v225
	v_mov_b32_e32 v130, v226
	v_mov_b32_e32 v131, v227
	v_mov_b32_e32 v132, v228
	v_mov_b32_e32 v133, v229
	v_mov_b32_e32 v134, v230
	v_mov_b32_e32 v135, v231
	v_lshlrev_b32_e32 v176, 16, v128
	v_lshlrev_b32_e32 v147, 16, v132
	v_and_b32_e32 v132, 0xffff0000, v132
	v_and_b32_e32 v177, 0xffff0000, v128
	v_lshlrev_b32_e32 v128, 16, v133
	v_rcp_f32_e32 v175, v132
	v_rcp_f32_e32 v132, v128
	v_and_b32_e32 v128, 0xffff0000, v133
	v_rcp_f32_e32 v133, v128
	v_lshlrev_b32_e32 v128, 16, v129
	v_and_b32_e32 v129, 0xffff0000, v129
	v_rcp_f32_e32 v174, v147
	v_pk_mul_f32 v[128:129], v[132:133], v[128:129]
	v_lshlrev_b32_e32 v132, 16, v130
	v_pk_mul_f32 v[38:39], v[38:39], v[128:129]
	v_lshlrev_b32_e32 v128, 16, v134
	v_and_b32_e32 v129, 0xffff0000, v134
	v_rcp_f32_e32 v128, v128
	v_rcp_f32_e32 v129, v129
	v_and_b32_e32 v133, 0xffff0000, v130
	v_lshlrev_b32_e32 v130, 16, v131
	v_and_b32_e32 v131, 0xffff0000, v131
	v_pk_mul_f32 v[128:129], v[128:129], v[132:133]
	v_pk_mul_f32 v[174:175], v[174:175], v[176:177]
	v_pk_mul_f32 v[32:33], v[32:33], v[128:129]
	v_lshlrev_b32_e32 v128, 16, v135
	v_and_b32_e32 v129, 0xffff0000, v135
	v_rcp_f32_e32 v128, v128
	v_rcp_f32_e32 v129, v129
	v_pk_mul_f32 v[36:37], v[36:37], v[174:175]
	v_pk_mul_f32 v[128:129], v[128:129], v[130:131]
	s_nop 0
	v_pk_mul_f32 v[34:35], v[34:35], v[128:129]
	v_lshl_add_u64 v[128:129], s[36:37], 0, v[164:165]
	v_lshl_add_u64 v[132:133], v[128:129], 0, v[168:169]
	s_waitcnt vmcnt(6)
	v_mov_b32_e32 v128, v234
	v_mov_b32_e32 v129, v235
	v_mov_b32_e32 v130, v236
	v_mov_b32_e32 v131, v237
	v_mov_b32_e32 v174, v238
	v_mov_b32_e32 v175, v239
	v_mov_b32_e32 v176, v240
	v_mov_b32_e32 v177, v241
	v_lshlrev_b32_e32 v178, 16, v128
	v_lshlrev_b32_e32 v134, 16, v174
	v_and_b32_e32 v135, 0xffff0000, v174
	v_rcp_f32_e32 v134, v134
	v_rcp_f32_e32 v135, v135
	v_and_b32_e32 v179, 0xffff0000, v128
	v_lshlrev_b32_e32 v128, 16, v175
	v_pk_mul_f32 v[134:135], v[134:135], v[178:179]
	s_nop 0
	v_pk_mul_f32 v[28:29], v[28:29], v[134:135]
	v_rcp_f32_e32 v134, v128
	v_and_b32_e32 v128, 0xffff0000, v175
	v_rcp_f32_e32 v135, v128
	v_lshlrev_b32_e32 v128, 16, v129
	v_and_b32_e32 v129, 0xffff0000, v129
	v_pk_mul_f32 v[128:129], v[134:135], v[128:129]
	s_nop 0
	v_pk_mul_f32 v[30:31], v[30:31], v[128:129]
	v_lshlrev_b32_e32 v128, 16, v176
	v_and_b32_e32 v129, 0xffff0000, v176
	v_rcp_f32_e32 v128, v128
	v_rcp_f32_e32 v129, v129
	v_lshlrev_b32_e32 v134, 16, v130
	v_and_b32_e32 v135, 0xffff0000, v130
	v_lshlrev_b32_e32 v130, 16, v131
	v_pk_mul_f32 v[128:129], v[128:129], v[134:135]
	v_and_b32_e32 v131, 0xffff0000, v131
	v_pk_mul_f32 v[24:25], v[24:25], v[128:129]
	v_lshlrev_b32_e32 v128, 16, v177
	v_and_b32_e32 v129, 0xffff0000, v177
	v_rcp_f32_e32 v128, v128
	v_rcp_f32_e32 v129, v129
	s_nop 0
	v_pk_mul_f32 v[128:129], v[128:129], v[130:131]
	s_nop 0
	v_pk_mul_f32 v[26:27], v[26:27], v[128:129]
	s_nop 0
	s_waitcnt vmcnt(4)
;     __device__ __forceinline__ void khook(f32x4 (&acc)[2][2][4][2], const Unit& u, int t, int wr, int wc, int fr, int fq) const {
;         const int br = t >> 4; const bf16_t* gates = (const bf16_t*)(ws + WS_GATES) + br * 1024;
;         const int row0 = u.pm * BM + wr * 64 + fr, cw = wc * 32 + 8 * fq;
; #pragma unroll
;         for (int ai = 0; ai < 2; ++ai)
; #pragma unroll
;             for (int m = 0; m < 4; ++m) { const int row = row0 + ai * HALF + m * 16;
; #pragma unroll
;                 for (int bj = 0; bj < 2; ++bj) { const int C0 = u.pn * 256 + bj * HALF + cw;
;                     const u32x4 ga = *(const u32x4*)(gates + (size_t)row * 3072 + C0), gb = *(const u32x4*)(gates + (size_t)row * 3072 + 1024 + C0);
;                     f32x4& v0 = acc[ai][bj][m][0]; f32x4& v1 = acc[ai][bj][m][1];
;                     v0[0] *= bflo(ga.x) * __builtin_amdgcn_rcpf(bflo(gb.x)); v0[1] *= bfhi(ga.x) * __builtin_amdgcn_rcpf(bfhi(gb.x)); v0[2] *= bflo(ga.y) * __builtin_amdgcn_rcpf(bflo(gb.y)); v0[3] *= bfhi(ga.y) * __builtin_amdgcn_rcpf(bfhi(gb.y));
;                     v1[0] *= bflo(ga.z) * __builtin_amdgcn_rcpf(bflo(gb.z)); v1[1] *= bfhi(ga.z) * __builtin_amdgcn_rcpf(bfhi(gb.z)); v1[2] *= bflo(ga.w) * __builtin_amdgcn_rcpf(bflo(gb.w)); v1[3] *= bfhi(ga.w) * __builtin_amdgcn_rcpf(bfhi(gb.w)); } }
;     }
	v_mov_b32_e32 v128, v242
	v_mov_b32_e32 v129, v243
	v_mov_b32_e32 v130, v244
	v_mov_b32_e32 v131, v245
	v_mov_b32_e32 v132, v246
	v_mov_b32_e32 v133, v247
	v_mov_b32_e32 v134, v248
	v_mov_b32_e32 v135, v249
	v_lshlrev_b32_e32 v176, 16, v128
	v_lshlrev_b32_e32 v147, 16, v132
	v_and_b32_e32 v132, 0xffff0000, v132
	v_and_b32_e32 v177, 0xffff0000, v128
	v_lshlrev_b32_e32 v128, 16, v133
	v_rcp_f32_e32 v175, v132
	v_rcp_f32_e32 v132, v128
	v_and_b32_e32 v128, 0xffff0000, v133
	v_rcp_f32_e32 v133, v128
	v_lshlrev_b32_e32 v128, 16, v129
	v_and_b32_e32 v129, 0xffff0000, v129
	v_rcp_f32_e32 v174, v147
	v_pk_mul_f32 v[128:129], v[132:133], v[128:129]
	v_lshlrev_b32_e32 v132, 16, v130
	v_pk_mul_f32 v[22:23], v[22:23], v[128:129]
	v_lshlrev_b32_e32 v128, 16, v134
	v_and_b32_e32 v129, 0xffff0000, v134
	v_rcp_f32_e32 v128, v128
	v_rcp_f32_e32 v129, v129
	v_and_b32_e32 v133, 0xffff0000, v130
	v_lshlrev_b32_e32 v130, 16, v131
	v_and_b32_e32 v131, 0xffff0000, v131
	v_pk_mul_f32 v[128:129], v[128:129], v[132:133]
	v_pk_mul_f32 v[174:175], v[174:175], v[176:177]
	v_pk_mul_f32 v[16:17], v[16:17], v[128:129]
	v_lshlrev_b32_e32 v128, 16, v135
	v_and_b32_e32 v129, 0xffff0000, v135
	v_rcp_f32_e32 v128, v128
	v_rcp_f32_e32 v129, v129
	v_pk_mul_f32 v[20:21], v[20:21], v[174:175]
	v_pk_mul_f32 v[128:129], v[128:129], v[130:131]
	s_nop 0
	v_pk_mul_f32 v[18:19], v[18:19], v[128:129]
	v_lshl_add_u64 v[128:129], s[36:37], 0, v[166:167]
	v_lshl_add_u64 v[132:133], v[128:129], 0, v[168:169]
	s_waitcnt vmcnt(2)
	v_mov_b32_e32 v128, v180
	v_mov_b32_e32 v129, v181
	v_mov_b32_e32 v130, v182
	v_mov_b32_e32 v131, v183
	v_mov_b32_e32 v174, v184
	v_mov_b32_e32 v175, v185
	v_mov_b32_e32 v176, v186
	v_mov_b32_e32 v177, v187
	v_lshlrev_b32_e32 v178, 16, v128
	v_lshlrev_b32_e32 v134, 16, v174
	v_and_b32_e32 v135, 0xffff0000, v174
	v_rcp_f32_e32 v134, v134
	v_rcp_f32_e32 v135, v135
	v_and_b32_e32 v179, 0xffff0000, v128
	v_lshlrev_b32_e32 v128, 16, v175
	v_pk_mul_f32 v[134:135], v[134:135], v[178:179]
	s_nop 0
	v_pk_mul_f32 v[12:13], v[12:13], v[134:135]
	v_rcp_f32_e32 v134, v128
	v_and_b32_e32 v128, 0xffff0000, v175
	v_rcp_f32_e32 v135, v128
	v_lshlrev_b32_e32 v128, 16, v129
	v_and_b32_e32 v129, 0xffff0000, v129
	v_pk_mul_f32 v[128:129], v[134:135], v[128:129]
	s_nop 0
	v_pk_mul_f32 v[14:15], v[14:15], v[128:129]
	v_lshlrev_b32_e32 v128, 16, v176
	v_and_b32_e32 v129, 0xffff0000, v176
	v_rcp_f32_e32 v128, v128
	v_rcp_f32_e32 v129, v129
	v_lshlrev_b32_e32 v134, 16, v130
	v_and_b32_e32 v135, 0xffff0000, v130
	v_lshlrev_b32_e32 v130, 16, v131
	v_pk_mul_f32 v[128:129], v[128:129], v[134:135]
	v_and_b32_e32 v131, 0xffff0000, v131
	v_pk_mul_f32 v[8:9], v[8:9], v[128:129]
	v_lshlrev_b32_e32 v128, 16, v177
	v_and_b32_e32 v129, 0xffff0000, v177
	v_rcp_f32_e32 v128, v128
	v_rcp_f32_e32 v129, v129
	s_nop 0
	v_pk_mul_f32 v[128:129], v[128:129], v[130:131]
	s_nop 0
	v_pk_mul_f32 v[10:11], v[10:11], v[128:129]
	s_nop 0
	s_waitcnt vmcnt(0)
	v_mov_b32_e32 v128, v188
	v_mov_b32_e32 v129, v189
	v_mov_b32_e32 v130, v190
	v_mov_b32_e32 v131, v191
	v_mov_b32_e32 v132, v192
	v_mov_b32_e32 v133, v193
	v_mov_b32_e32 v134, v194
	v_mov_b32_e32 v135, v195
	v_lshlrev_b32_e32 v176, 16, v128
	v_lshlrev_b32_e32 v147, 16, v132
	v_and_b32_e32 v132, 0xffff0000, v132
	v_and_b32_e32 v177, 0xffff0000, v128
	v_lshlrev_b32_e32 v128, 16, v133
	v_rcp_f32_e32 v175, v132
	v_rcp_f32_e32 v132, v128
	v_and_b32_e32 v128, 0xffff0000, v133
	v_rcp_f32_e32 v133, v128
	v_lshlrev_b32_e32 v128, 16, v129
	v_and_b32_e32 v129, 0xffff0000, v129
	v_rcp_f32_e32 v174, v147
	v_pk_mul_f32 v[128:129], v[132:133], v[128:129]
	v_lshlrev_b32_e32 v132, 16, v130
	v_pk_mul_f32 v[6:7], v[6:7], v[128:129]
	v_lshlrev_b32_e32 v128, 16, v134
	v_and_b32_e32 v129, 0xffff0000, v134
	v_rcp_f32_e32 v128, v128
	v_rcp_f32_e32 v129, v129
	v_and_b32_e32 v133, 0xffff0000, v130
	v_lshlrev_b32_e32 v130, 16, v131
	v_and_b32_e32 v131, 0xffff0000, v131
	v_pk_mul_f32 v[128:129], v[128:129], v[132:133]
	v_pk_mul_f32 v[174:175], v[174:175], v[176:177]
	v_pk_mul_f32 v[0:1], v[0:1], v[128:129]
	v_lshlrev_b32_e32 v128, 16, v135
	v_and_b32_e32 v129, 0xffff0000, v135
	v_rcp_f32_e32 v128, v128
	v_rcp_f32_e32 v129, v129
	v_pk_mul_f32 v[4:5], v[4:5], v[174:175]
	v_pk_mul_f32 v[128:129], v[128:129], v[130:131]
	s_nop 0
	v_pk_mul_f32 v[2:3], v[2:3], v[128:129]

;     __device__ __forceinline__ static u32x4 pack8(const f32x4& a, const f32x4& b) { u32x4 w; w.x = cvtpk(a[0], a[1]); w.y = cvtpk(a[2], a[3]); w.z = cvtpk(b[0], b[1]); w.w = cvtpk(b[2], b[3]); return w; }
;     __device__ __forceinline__ void operator()(const f32x4 (&acc)[2][2][4][2], const Unit& u, int wr, int wc, int fr, int fq) const {
;     ...
;         } else if (mode == EM_MRG) {
;             const bf16_t* gates = (const bf16_t*)(ws + WS_GATES); bf16_t* mrg = (bf16_t*)(ws + WS_MRG);
; #pragma unroll
;             for (int ai = 0; ai < 2; ++ai)
; #pragma unroll
;                 for (int m = 0; m < 4; ++m) { const int row = row0 + ai * HALF + m * 16;
; #pragma unroll
;                     for (int bj = 0; bj < 2; ++bj) { const int C0 = pn * 256 + bj * HALF + cw;
;                         const u32x4 g = *(const u32x4*)(gates + (size_t)row * 3072 + 2048 + C0);
;                         f32x4 v0 = acc[ai][bj][m][0], v1 = acc[ai][bj][m][1];
;                         v0[0] *= bflo(g.x); v0[1] *= bfhi(g.x); v0[2] *= bflo(g.y); v0[3] *= bfhi(g.y); v1[0] *= bflo(g.z); v1[1] *= bfhi(g.z); v1[2] *= bflo(g.w); v1[3] *= bfhi(g.w);
;                         *(u32x4*)(mrg + (size_t)row * 1024 + C0) = pack8(v0, v1); } }
.LBB0_1110:
	v_mov_b64_e32 v[130:131], s[12:13]
	v_ashrrev_i32_e32 v147, 31, v146
	v_mad_i64_i32 v[128:129], s[2:3], v146, s89, v[130:131]
	s_mov_b64 s[4:5], 0x12e01000
	v_ashrrev_i32_e32 v151, 31, v150
	v_lshl_add_u64 v[152:153], v[128:129], 0, s[4:5]
	v_lshlrev_b64 v[128:129], 11, v[146:147]
	v_lshl_add_u64 v[154:155], s[24:25], 0, v[128:129]
	v_lshlrev_b64 v[128:129], 1, v[150:151]
	v_lshl_add_u64 v[132:133], v[152:153], 0, v[128:129]
	v_lshl_add_u64 v[208:209], v[152:153], 0, v[128:129]
	global_load_dwordx4 v[192:195], v[208:209], off
	global_load_dwordx4 v[196:199], v[208:209], off offset:256
	s_mov_b32 s98, 0x18000
	s_mov_b32 s99, 0
	v_lshl_add_u64 v[204:205], v[208:209], 0, s[98:99]
	global_load_dwordx4 v[200:203], v[204:205], off
	global_load_dwordx4 v[216:219], v[204:205], off offset:256
	s_mov_b32 s98, 0x30000
	s_mov_b32 s99, 0
	v_lshl_add_u64 v[204:205], v[208:209], 0, s[98:99]
	global_load_dwordx4 v[220:223], v[204:205], off
	global_load_dwordx4 v[224:227], v[204:205], off offset:256
	s_mov_b32 s98, 0x48000
	s_mov_b32 s99, 0
	v_lshl_add_u64 v[204:205], v[208:209], 0, s[98:99]
	global_load_dwordx4 v[228:231], v[204:205], off
	global_load_dwordx4 v[234:237], v[204:205], off offset:256
	s_mov_b32 s98, 0xc0000
	s_mov_b32 s99, 0
	v_lshl_add_u64 v[204:205], v[208:209], 0, s[98:99]
	global_load_dwordx4 v[238:241], v[204:205], off
	global_load_dwordx4 v[242:245], v[204:205], off offset:256
	s_mov_b32 s98, 0xd8000
	s_mov_b32 s99, 0
	v_lshl_add_u64 v[204:205], v[208:209], 0, s[98:99]
	global_load_dwordx4 v[246:249], v[204:205], off
	global_load_dwordx4 v[250:253], v[204:205], off offset:256
	s_and_b64 vcc, exec, s[6:7]
	s_waitcnt vmcnt(11)
	v_mov_b32_e32 v132, v192
	v_mov_b32_e32 v133, v193
	v_mov_b32_e32 v134, v194
	v_mov_b32_e32 v135, v195
	s_mov_b32 s98, 0xf0000
	s_mov_b32 s99, 0
	v_lshl_add_u64 v[204:205], v[208:209], 0, s[98:99]
	global_load_dwordx4 v[192:195], v[204:205], off
	v_lshlrev_b32_e32 v156, 16, v132
	v_and_b32_e32 v157, 0xffff0000, v132
	v_lshlrev_b32_e32 v132, 16, v133
	v_and_b32_e32 v133, 0xffff0000, v133
	v_pk_mul_f32 v[126:127], v[126:127], v[132:133]
	v_lshlrev_b32_e32 v132, 16, v134
	v_and_b32_e32 v133, 0xffff0000, v134
	v_pk_mul_f32 v[132:133], v[120:121], v[132:133]
	v_lshlrev_b32_e32 v120, 16, v135
	v_and_b32_e32 v121, 0xffff0000, v135
	v_pk_mul_f32 v[124:125], v[124:125], v[156:157]
	v_pk_mul_f32 v[134:135], v[122:123], v[120:121]
	v_cvt_pk_bf16_f32 v120, v124, v125
	v_cvt_pk_bf16_f32 v121, v126, v127
	v_cvt_pk_bf16_f32 v122, v132, v133
	v_cvt_pk_bf16_f32 v123, v134, v135
	v_lshl_add_u64 v[126:127], v[154:155], 0, v[128:129]
	global_store_dwordx4 v[126:127], v[120:123], off
	s_nop 1
	v_or_b32_e32 v120, 0x80, v150
	v_ashrrev_i32_e32 v121, 31, v120
	v_lshlrev_b64 v[120:121], 1, v[120:121]
	v_lshl_add_u64 v[122:123], v[152:153], 0, v[120:121]
	s_waitcnt vmcnt(12)
	v_mov_b32_e32 v122, v196
	v_mov_b32_e32 v123, v197
	v_mov_b32_e32 v124, v198
	v_mov_b32_e32 v125, v199
	global_load_dwordx4 v[196:199], v[204:205], off offset:256
	v_lshlrev_b32_e32 v132, 16, v122
	v_and_b32_e32 v133, 0xffff0000, v122
	v_lshlrev_b32_e32 v122, 16, v123
	v_and_b32_e32 v123, 0xffff0000, v123
	v_pk_mul_f32 v[118:119], v[118:119], v[122:123]
	v_lshlrev_b32_e32 v122, 16, v124
	v_and_b32_e32 v123, 0xffff0000, v124
	v_pk_mul_f32 v[122:123], v[112:113], v[122:123]
	v_lshlrev_b32_e32 v112, 16, v125
	v_and_b32_e32 v113, 0xffff0000, v125
	v_pk_mul_f32 v[116:117], v[116:117], v[132:133]
	v_pk_mul_f32 v[124:125], v[114:115], v[112:113]
	v_cvt_pk_bf16_f32 v112, v116, v117
	v_cvt_pk_bf16_f32 v113, v118, v119
	v_cvt_pk_bf16_f32 v114, v122, v123
	v_cvt_pk_bf16_f32 v115, v124, v125
	global_store_dwordx4 v[126:127], v[112:115], off offset:256
	s_nop 1
	v_or_b32_e32 v112, 16, v146
	v_ashrrev_i32_e32 v113, 31, v112
	v_mad_i64_i32 v[114:115], s[2:3], v112, s89, v[130:131]
	v_lshl_add_u64 v[116:117], v[114:115], 0, s[4:5]
	v_lshlrev_b64 v[112:113], 11, v[112:113]
	v_lshl_add_u64 v[118:119], s[24:25], 0, v[112:113]
	v_lshl_add_u64 v[112:113], v[116:117], 0, v[128:129]
	s_waitcnt vmcnt(13)
	v_mov_b32_e32 v112, v200
	v_mov_b32_e32 v113, v201
	v_mov_b32_e32 v114, v202
	v_mov_b32_e32 v115, v203
	s_mov_b32 s98, 0x108000
	s_mov_b32 s99, 0
	v_lshl_add_u64 v[204:205], v[208:209], 0, s[98:99]
	global_load_dwordx4 v[200:203], v[204:205], off
	v_lshlrev_b32_e32 v122, 16, v112
	v_and_b32_e32 v123, 0xffff0000, v112
	v_lshlrev_b32_e32 v112, 16, v113
	v_and_b32_e32 v113, 0xffff0000, v113
	v_pk_mul_f32 v[110:111], v[110:111], v[112:113]
	v_lshlrev_b32_e32 v112, 16, v114
	v_and_b32_e32 v113, 0xffff0000, v114
	v_pk_mul_f32 v[104:105], v[104:105], v[112:113]
	v_lshlrev_b32_e32 v112, 16, v115
	v_and_b32_e32 v113, 0xffff0000, v115
	v_pk_mul_f32 v[108:109], v[108:109], v[122:123]
	v_pk_mul_f32 v[112:113], v[106:107], v[112:113]
	v_cvt_pk_bf16_f32 v106, v108, v109
	v_cvt_pk_bf16_f32 v107, v110, v111
	v_cvt_pk_bf16_f32 v108, v104, v105
	v_cvt_pk_bf16_f32 v109, v112, v113
	v_lshl_add_u64 v[104:105], v[118:119], 0, v[128:129]
	global_store_dwordx4 v[104:105], v[106:109], off
	s_nop 1
	v_lshl_add_u64 v[106:107], v[116:117], 0, v[120:121]
	s_waitcnt vmcnt(14)
;     __device__ __forceinline__ static u32x4 pack8(const f32x4& a, const f32x4& b) { u32x4 w; w.x = cvtpk(a[0], a[1]); w.y = cvtpk(a[2], a[3]); w.z = cvtpk(b[0], b[1]); w.w = cvtpk(b[2], b[3]); return w; }
;     __device__ __forceinline__ void operator()(const f32x4 (&acc)[2][2][4][2], const Unit& u, int wr, int wc, int fr, int fq) const {
;     ...
;         } else if (mode == EM_MRG) {
;             const bf16_t* gates = (const bf16_t*)(ws + WS_GATES); bf16_t* mrg = (bf16_t*)(ws + WS_MRG);
; #pragma unroll
;             for (int ai = 0; ai < 2; ++ai)
; #pragma unroll
;                 for (int m = 0; m < 4; ++m) { const int row = row0 + ai * HALF + m * 16;
; #pragma unroll
;                     for (int bj = 0; bj < 2; ++bj) { const int C0 = pn * 256 + bj * HALF + cw;
;                         const u32x4 g = *(const u32x4*)(gates + (size_t)row * 3072 + 2048 + C0);
;                         f32x4 v0 = acc[ai][bj][m][0], v1 = acc[ai][bj][m][1];
;                         v0[0] *= bflo(g.x); v0[1] *= bfhi(g.x); v0[2] *= bflo(g.y); v0[3] *= bfhi(g.y); v1[0] *= bflo(g.z); v1[1] *= bfhi(g.z); v1[2] *= bflo(g.w); v1[3] *= bfhi(g.w);
;                         *(u32x4*)(mrg + (size_t)row * 1024 + C0) = pack8(v0, v1); } }
	v_mov_b32_e32 v106, v216
	v_mov_b32_e32 v107, v217
	v_mov_b32_e32 v108, v218
	v_mov_b32_e32 v109, v219
	global_load_dwordx4 v[216:219], v[204:205], off offset:256
	v_lshlrev_b32_e32 v110, 16, v106
	v_and_b32_e32 v111, 0xffff0000, v106
	v_lshlrev_b32_e32 v106, 16, v107
	v_and_b32_e32 v107, 0xffff0000, v107
	v_pk_mul_f32 v[102:103], v[102:103], v[106:107]
	v_lshlrev_b32_e32 v106, 16, v108
	v_and_b32_e32 v107, 0xffff0000, v108
	v_pk_mul_f32 v[106:107], v[96:97], v[106:107]
	v_lshlrev_b32_e32 v96, 16, v109
	v_and_b32_e32 v97, 0xffff0000, v109
	v_pk_mul_f32 v[100:101], v[100:101], v[110:111]
	v_pk_mul_f32 v[108:109], v[98:99], v[96:97]
	v_cvt_pk_bf16_f32 v96, v100, v101
	v_cvt_pk_bf16_f32 v97, v102, v103
	v_cvt_pk_bf16_f32 v98, v106, v107
	v_cvt_pk_bf16_f32 v99, v108, v109
	global_store_dwordx4 v[104:105], v[96:99], off offset:256
	s_nop 1
	v_or_b32_e32 v96, 32, v146
	v_ashrrev_i32_e32 v97, 31, v96
	v_mad_i64_i32 v[98:99], s[2:3], v96, s89, v[130:131]
	v_lshl_add_u64 v[100:101], v[98:99], 0, s[4:5]
	v_lshlrev_b64 v[96:97], 11, v[96:97]
	v_lshl_add_u64 v[102:103], s[24:25], 0, v[96:97]
	v_lshl_add_u64 v[96:97], v[100:101], 0, v[128:129]
	s_waitcnt vmcnt(15)
	v_mov_b32_e32 v96, v220
	v_mov_b32_e32 v97, v221
	v_mov_b32_e32 v98, v222
	v_mov_b32_e32 v99, v223
	v_lshlrev_b32_e32 v104, 16, v96
	v_and_b32_e32 v105, 0xffff0000, v96
	v_lshlrev_b32_e32 v96, 16, v97
	v_and_b32_e32 v97, 0xffff0000, v97
	v_pk_mul_f32 v[94:95], v[94:95], v[96:97]
	v_lshlrev_b32_e32 v96, 16, v98
	v_and_b32_e32 v97, 0xffff0000, v98
	v_pk_mul_f32 v[88:89], v[88:89], v[96:97]
	v_lshlrev_b32_e32 v96, 16, v99
	v_and_b32_e32 v97, 0xffff0000, v99
	v_pk_mul_f32 v[92:93], v[92:93], v[104:105]
	v_pk_mul_f32 v[96:97], v[90:91], v[96:97]
	v_cvt_pk_bf16_f32 v90, v92, v93
	v_cvt_pk_bf16_f32 v91, v94, v95
	v_cvt_pk_bf16_f32 v92, v88, v89
	v_cvt_pk_bf16_f32 v93, v96, v97
	v_lshl_add_u64 v[88:89], v[102:103], 0, v[128:129]
	global_store_dwordx4 v[88:89], v[90:93], off
	s_nop 1
	v_lshl_add_u64 v[90:91], v[100:101], 0, v[120:121]
	s_waitcnt vmcnt(15)
	v_mov_b32_e32 v90, v224
	v_mov_b32_e32 v91, v225
	v_mov_b32_e32 v92, v226
	v_mov_b32_e32 v93, v227
	v_lshlrev_b32_e32 v94, 16, v90
	v_and_b32_e32 v95, 0xffff0000, v90
	v_lshlrev_b32_e32 v90, 16, v91
	v_and_b32_e32 v91, 0xffff0000, v91
	v_pk_mul_f32 v[86:87], v[86:87], v[90:91]
	v_lshlrev_b32_e32 v90, 16, v92
	v_and_b32_e32 v91, 0xffff0000, v92
	v_pk_mul_f32 v[90:91], v[80:81], v[90:91]
	v_lshlrev_b32_e32 v80, 16, v93
	v_and_b32_e32 v81, 0xffff0000, v93
	v_pk_mul_f32 v[84:85], v[84:85], v[94:95]
	v_pk_mul_f32 v[92:93], v[82:83], v[80:81]
	v_cvt_pk_bf16_f32 v80, v84, v85
	v_cvt_pk_bf16_f32 v81, v86, v87
	v_cvt_pk_bf16_f32 v82, v90, v91
	v_cvt_pk_bf16_f32 v83, v92, v93
	global_store_dwordx4 v[88:89], v[80:83], off offset:256
	s_nop 1
	v_or_b32_e32 v80, 48, v146
	v_ashrrev_i32_e32 v81, 31, v80
	v_mad_i64_i32 v[82:83], s[2:3], v80, s89, v[130:131]
	v_lshl_add_u64 v[84:85], v[82:83], 0, s[4:5]
	v_lshlrev_b64 v[80:81], 11, v[80:81]
	v_lshl_add_u64 v[86:87], s[24:25], 0, v[80:81]
	v_lshl_add_u64 v[80:81], v[84:85], 0, v[128:129]
	s_waitcnt vmcnt(15)
	v_mov_b32_e32 v80, v228
	v_mov_b32_e32 v81, v229
	v_mov_b32_e32 v82, v230
	v_mov_b32_e32 v83, v231
	v_lshlrev_b32_e32 v88, 16, v80
	v_and_b32_e32 v89, 0xffff0000, v80
	v_lshlrev_b32_e32 v80, 16, v81
	v_and_b32_e32 v81, 0xffff0000, v81
	v_pk_mul_f32 v[78:79], v[78:79], v[80:81]
	v_lshlrev_b32_e32 v80, 16, v82
	v_and_b32_e32 v81, 0xffff0000, v82
	v_pk_mul_f32 v[72:73], v[72:73], v[80:81]
	v_lshlrev_b32_e32 v80, 16, v83
	v_and_b32_e32 v81, 0xffff0000, v83
	v_pk_mul_f32 v[76:77], v[76:77], v[88:89]
	v_pk_mul_f32 v[80:81], v[74:75], v[80:81]
	v_cvt_pk_bf16_f32 v74, v76, v77
	v_cvt_pk_bf16_f32 v75, v78, v79
	v_cvt_pk_bf16_f32 v76, v72, v73
	v_cvt_pk_bf16_f32 v77, v80, v81
	v_lshl_add_u64 v[72:73], v[86:87], 0, v[128:129]
	global_store_dwordx4 v[72:73], v[74:77], off
	s_nop 1
	v_lshl_add_u64 v[74:75], v[84:85], 0, v[120:121]
	s_waitcnt vmcnt(15)
	v_mov_b32_e32 v74, v234
	v_mov_b32_e32 v75, v235
	v_mov_b32_e32 v76, v236
	v_mov_b32_e32 v77, v237
	v_lshlrev_b32_e32 v78, 16, v74
	v_and_b32_e32 v79, 0xffff0000, v74
	v_lshlrev_b32_e32 v74, 16, v75
	v_and_b32_e32 v75, 0xffff0000, v75
	v_pk_mul_f32 v[70:71], v[70:71], v[74:75]
	v_lshlrev_b32_e32 v74, 16, v76
	v_and_b32_e32 v75, 0xffff0000, v76
	v_pk_mul_f32 v[74:75], v[64:65], v[74:75]
	v_lshlrev_b32_e32 v64, 16, v77
	v_and_b32_e32 v65, 0xffff0000, v77
	v_pk_mul_f32 v[68:69], v[68:69], v[78:79]
	v_pk_mul_f32 v[76:77], v[66:67], v[64:65]
	v_cvt_pk_bf16_f32 v64, v68, v69
	v_cvt_pk_bf16_f32 v65, v70, v71
	v_cvt_pk_bf16_f32 v66, v74, v75
	v_cvt_pk_bf16_f32 v67, v76, v77
	global_store_dwordx4 v[72:73], v[64:67], off offset:256
	s_nop 1
	v_add_u32_e32 v64, 0x80, v146
	v_ashrrev_i32_e32 v65, 31, v64
	v_mad_i64_i32 v[66:67], s[2:3], v64, s89, v[130:131]
	v_lshl_add_u64 v[68:69], v[66:67], 0, s[4:5]
	v_lshlrev_b64 v[64:65], 11, v[64:65]
	v_lshl_add_u64 v[70:71], s[24:25], 0, v[64:65]
	v_lshl_add_u64 v[64:65], v[68:69], 0, v[128:129]
	s_waitcnt vmcnt(15)
	v_mov_b32_e32 v64, v238
	v_mov_b32_e32 v65, v239
	v_mov_b32_e32 v66, v240
	v_mov_b32_e32 v67, v241
	v_lshlrev_b32_e32 v72, 16, v64
	v_and_b32_e32 v73, 0xffff0000, v64
	v_lshlrev_b32_e32 v64, 16, v65
	v_and_b32_e32 v65, 0xffff0000, v65
	v_pk_mul_f32 v[62:63], v[62:63], v[64:65]
	v_lshlrev_b32_e32 v64, 16, v66
	v_and_b32_e32 v65, 0xffff0000, v66
	v_pk_mul_f32 v[56:57], v[56:57], v[64:65]
	v_lshlrev_b32_e32 v64, 16, v67
	v_and_b32_e32 v65, 0xffff0000, v67
	v_pk_mul_f32 v[60:61], v[60:61], v[72:73]
	v_pk_mul_f32 v[64:65], v[58:59], v[64:65]
	v_cvt_pk_bf16_f32 v58, v60, v61
	v_cvt_pk_bf16_f32 v59, v62, v63
	v_cvt_pk_bf16_f32 v60, v56, v57
	v_cvt_pk_bf16_f32 v61, v64, v65
	v_lshl_add_u64 v[56:57], v[70:71], 0, v[128:129]
	global_store_dwordx4 v[56:57], v[58:61], off
	s_nop 1
	v_lshl_add_u64 v[58:59], v[68:69], 0, v[120:121]
	s_waitcnt vmcnt(15)
;     __device__ __forceinline__ static u32x4 pack8(const f32x4& a, const f32x4& b) { u32x4 w; w.x = cvtpk(a[0], a[1]); w.y = cvtpk(a[2], a[3]); w.z = cvtpk(b[0], b[1]); w.w = cvtpk(b[2], b[3]); return w; }
;     __device__ __forceinline__ void operator()(const f32x4 (&acc)[2][2][4][2], const Unit& u, int wr, int wc, int fr, int fq) const {
;     ...
;         } else if (mode == EM_MRG) {
;             const bf16_t* gates = (const bf16_t*)(ws + WS_GATES); bf16_t* mrg = (bf16_t*)(ws + WS_MRG);
; #pragma unroll
;             for (int ai = 0; ai < 2; ++ai)
; #pragma unroll
;                 for (int m = 0; m < 4; ++m) { const int row = row0 + ai * HALF + m * 16;
; #pragma unroll
;                     for (int bj = 0; bj < 2; ++bj) { const int C0 = pn * 256 + bj * HALF + cw;
;                         const u32x4 g = *(const u32x4*)(gates + (size_t)row * 3072 + 2048 + C0);
;                         f32x4 v0 = acc[ai][bj][m][0], v1 = acc[ai][bj][m][1];
;                         v0[0] *= bflo(g.x); v0[1] *= bfhi(g.x); v0[2] *= bflo(g.y); v0[3] *= bfhi(g.y); v1[0] *= bflo(g.z); v1[1] *= bfhi(g.z); v1[2] *= bflo(g.w); v1[3] *= bfhi(g.w);
;                         *(u32x4*)(mrg + (size_t)row * 1024 + C0) = pack8(v0, v1); } }
	v_mov_b32_e32 v58, v242
	v_mov_b32_e32 v59, v243
	v_mov_b32_e32 v60, v244
	v_mov_b32_e32 v61, v245
	v_lshlrev_b32_e32 v62, 16, v58
	v_and_b32_e32 v63, 0xffff0000, v58
	v_lshlrev_b32_e32 v58, 16, v59
	v_and_b32_e32 v59, 0xffff0000, v59
	v_pk_mul_f32 v[54:55], v[54:55], v[58:59]
	v_lshlrev_b32_e32 v58, 16, v60
	v_and_b32_e32 v59, 0xffff0000, v60
	v_pk_mul_f32 v[58:59], v[48:49], v[58:59]
	v_lshlrev_b32_e32 v48, 16, v61
	v_and_b32_e32 v49, 0xffff0000, v61
	v_pk_mul_f32 v[52:53], v[52:53], v[62:63]
	v_pk_mul_f32 v[60:61], v[50:51], v[48:49]
	v_cvt_pk_bf16_f32 v48, v52, v53
	v_cvt_pk_bf16_f32 v49, v54, v55
	v_cvt_pk_bf16_f32 v50, v58, v59
	v_cvt_pk_bf16_f32 v51, v60, v61
	global_store_dwordx4 v[56:57], v[48:51], off offset:256
	s_nop 1
	v_add_u32_e32 v48, 0x90, v146
	v_ashrrev_i32_e32 v49, 31, v48
	v_mad_i64_i32 v[50:51], s[2:3], v48, s89, v[130:131]
	v_lshl_add_u64 v[52:53], v[50:51], 0, s[4:5]
	v_lshlrev_b64 v[48:49], 11, v[48:49]
	v_lshl_add_u64 v[54:55], s[24:25], 0, v[48:49]
	v_lshl_add_u64 v[48:49], v[52:53], 0, v[128:129]
	s_waitcnt vmcnt(15)
	v_mov_b32_e32 v48, v246
	v_mov_b32_e32 v49, v247
	v_mov_b32_e32 v50, v248
	v_mov_b32_e32 v51, v249
	v_lshlrev_b32_e32 v56, 16, v48
	v_and_b32_e32 v57, 0xffff0000, v48
	v_lshlrev_b32_e32 v48, 16, v49
	v_and_b32_e32 v49, 0xffff0000, v49
	v_pk_mul_f32 v[46:47], v[46:47], v[48:49]
	v_lshlrev_b32_e32 v48, 16, v50
	v_and_b32_e32 v49, 0xffff0000, v50
	v_pk_mul_f32 v[40:41], v[40:41], v[48:49]
	v_lshlrev_b32_e32 v48, 16, v51
	v_and_b32_e32 v49, 0xffff0000, v51
	v_pk_mul_f32 v[44:45], v[44:45], v[56:57]
	v_pk_mul_f32 v[48:49], v[42:43], v[48:49]
	v_cvt_pk_bf16_f32 v42, v44, v45
	v_cvt_pk_bf16_f32 v43, v46, v47
	v_cvt_pk_bf16_f32 v44, v40, v41
	v_cvt_pk_bf16_f32 v45, v48, v49
	v_lshl_add_u64 v[40:41], v[54:55], 0, v[128:129]
	global_store_dwordx4 v[40:41], v[42:45], off
	s_nop 1
	v_lshl_add_u64 v[42:43], v[52:53], 0, v[120:121]
	s_waitcnt vmcnt(15)
	v_mov_b32_e32 v42, v250
	v_mov_b32_e32 v43, v251
	v_mov_b32_e32 v44, v252
	v_mov_b32_e32 v45, v253
	v_lshlrev_b32_e32 v46, 16, v42
	v_and_b32_e32 v47, 0xffff0000, v42
	v_lshlrev_b32_e32 v42, 16, v43
	v_and_b32_e32 v43, 0xffff0000, v43
	v_pk_mul_f32 v[38:39], v[38:39], v[42:43]
	v_lshlrev_b32_e32 v42, 16, v44
	v_and_b32_e32 v43, 0xffff0000, v44
	v_pk_mul_f32 v[42:43], v[32:33], v[42:43]
	v_lshlrev_b32_e32 v32, 16, v45
	v_and_b32_e32 v33, 0xffff0000, v45
	v_pk_mul_f32 v[36:37], v[36:37], v[46:47]
	v_pk_mul_f32 v[44:45], v[34:35], v[32:33]
	v_cvt_pk_bf16_f32 v32, v36, v37
	v_cvt_pk_bf16_f32 v33, v38, v39
	v_cvt_pk_bf16_f32 v34, v42, v43
	v_cvt_pk_bf16_f32 v35, v44, v45
	global_store_dwordx4 v[40:41], v[32:35], off offset:256
	s_nop 1
	v_add_u32_e32 v32, 0xa0, v146
	v_ashrrev_i32_e32 v33, 31, v32
	v_mad_i64_i32 v[34:35], s[2:3], v32, s89, v[130:131]
	v_lshl_add_u64 v[36:37], v[34:35], 0, s[4:5]
	v_lshlrev_b64 v[32:33], 11, v[32:33]
	v_lshl_add_u64 v[38:39], s[24:25], 0, v[32:33]
	v_lshl_add_u64 v[32:33], v[36:37], 0, v[128:129]
	s_waitcnt vmcnt(15)
	v_mov_b32_e32 v32, v192
	v_mov_b32_e32 v33, v193
	v_mov_b32_e32 v34, v194
	v_mov_b32_e32 v35, v195
	v_lshlrev_b32_e32 v40, 16, v32
	v_and_b32_e32 v41, 0xffff0000, v32
	v_lshlrev_b32_e32 v32, 16, v33
	v_and_b32_e32 v33, 0xffff0000, v33
	v_pk_mul_f32 v[30:31], v[30:31], v[32:33]
	v_lshlrev_b32_e32 v32, 16, v34
	v_and_b32_e32 v33, 0xffff0000, v34
	v_pk_mul_f32 v[24:25], v[24:25], v[32:33]
	v_lshlrev_b32_e32 v32, 16, v35
	v_and_b32_e32 v33, 0xffff0000, v35
	v_pk_mul_f32 v[28:29], v[28:29], v[40:41]
	v_pk_mul_f32 v[32:33], v[26:27], v[32:33]
	v_cvt_pk_bf16_f32 v26, v28, v29
	v_cvt_pk_bf16_f32 v27, v30, v31
	v_cvt_pk_bf16_f32 v28, v24, v25
	v_cvt_pk_bf16_f32 v29, v32, v33
	v_lshl_add_u64 v[24:25], v[38:39], 0, v[128:129]
	global_store_dwordx4 v[24:25], v[26:29], off
	s_nop 1
	v_lshl_add_u64 v[26:27], v[36:37], 0, v[120:121]
	s_waitcnt vmcnt(14)
	v_mov_b32_e32 v26, v196
	v_mov_b32_e32 v27, v197
	v_mov_b32_e32 v28, v198
	v_mov_b32_e32 v29, v199
	v_lshlrev_b32_e32 v30, 16, v26
	v_and_b32_e32 v31, 0xffff0000, v26
	v_lshlrev_b32_e32 v26, 16, v27
	v_and_b32_e32 v27, 0xffff0000, v27
	v_pk_mul_f32 v[22:23], v[22:23], v[26:27]
	v_lshlrev_b32_e32 v26, 16, v28
	v_and_b32_e32 v27, 0xffff0000, v28
	v_pk_mul_f32 v[26:27], v[16:17], v[26:27]
	v_lshlrev_b32_e32 v16, 16, v29
	v_and_b32_e32 v17, 0xffff0000, v29
	v_pk_mul_f32 v[20:21], v[20:21], v[30:31]
	v_pk_mul_f32 v[28:29], v[18:19], v[16:17]
	v_cvt_pk_bf16_f32 v16, v20, v21
	v_cvt_pk_bf16_f32 v17, v22, v23
	v_cvt_pk_bf16_f32 v18, v26, v27
	v_cvt_pk_bf16_f32 v19, v28, v29
	global_store_dwordx4 v[24:25], v[16:19], off offset:256
	s_nop 1
	v_add_u32_e32 v16, 0xb0, v146
	v_ashrrev_i32_e32 v17, 31, v16
	v_mad_i64_i32 v[18:19], s[2:3], v16, s89, v[130:131]
	v_lshl_add_u64 v[20:21], v[18:19], 0, s[4:5]
	v_lshlrev_b64 v[16:17], 11, v[16:17]
	v_lshl_add_u64 v[22:23], s[24:25], 0, v[16:17]
	v_lshl_add_u64 v[16:17], v[20:21], 0, v[128:129]
	s_mov_b64 s[4:5], -1
	s_waitcnt vmcnt(13)
	v_mov_b32_e32 v16, v200
	v_mov_b32_e32 v17, v201
	v_mov_b32_e32 v18, v202
	v_mov_b32_e32 v19, v203
	v_lshlrev_b32_e32 v24, 16, v16
	v_and_b32_e32 v25, 0xffff0000, v16
	v_lshlrev_b32_e32 v16, 16, v17
	v_and_b32_e32 v17, 0xffff0000, v17
	v_pk_mul_f32 v[14:15], v[14:15], v[16:17]
	v_lshlrev_b32_e32 v16, 16, v18
	v_and_b32_e32 v17, 0xffff0000, v18
	v_pk_mul_f32 v[8:9], v[8:9], v[16:17]
	v_lshlrev_b32_e32 v16, 16, v19
	v_and_b32_e32 v17, 0xffff0000, v19
	v_pk_mul_f32 v[12:13], v[12:13], v[24:25]
	v_pk_mul_f32 v[16:17], v[10:11], v[16:17]
	v_cvt_pk_bf16_f32 v10, v12, v13
	v_cvt_pk_bf16_f32 v11, v14, v15
	v_cvt_pk_bf16_f32 v12, v8, v9
	v_cvt_pk_bf16_f32 v13, v16, v17
	v_lshl_add_u64 v[8:9], v[22:23], 0, v[128:129]
	global_store_dwordx4 v[8:9], v[10:13], off
	s_nop 1
	v_lshl_add_u64 v[10:11], v[20:21], 0, v[120:121]
	s_waitcnt vmcnt(12)
	v_mov_b32_e32 v10, v216
	v_mov_b32_e32 v11, v217
	v_mov_b32_e32 v12, v218
	v_mov_b32_e32 v13, v219
	v_lshlrev_b32_e32 v14, 16, v10
	v_and_b32_e32 v15, 0xffff0000, v10
	v_lshlrev_b32_e32 v10, 16, v11
	v_and_b32_e32 v11, 0xffff0000, v11
	v_pk_mul_f32 v[6:7], v[6:7], v[10:11]
	v_lshlrev_b32_e32 v10, 16, v12
	v_and_b32_e32 v11, 0xffff0000, v12
	v_pk_mul_f32 v[10:11], v[0:1], v[10:11]
	v_lshlrev_b32_e32 v0, 16, v13
	v_and_b32_e32 v1, 0xffff0000, v13
	v_pk_mul_f32 v[4:5], v[4:5], v[14:15]
	v_pk_mul_f32 v[12:13], v[2:3], v[0:1]
	v_cvt_pk_bf16_f32 v0, v4, v5
	v_cvt_pk_bf16_f32 v1, v6, v7
	v_cvt_pk_bf16_f32 v2, v10, v11
	v_cvt_pk_bf16_f32 v3, v12, v13
	global_store_dwordx4 v[8:9], v[0:3], off offset:256
	s_cbranch_vccnz .LBB0_1092
	s_andn2_b64 vcc, exec, s[22:23]
	s_cbranch_vccnz .LBB0_1091
	s_barrier
	s_branch .LBB0_1091

;     __device__ __forceinline__ static u32x4 pack8(const f32x4& a, const f32x4& b) { u32x4 w; w.x = cvtpk(a[0], a[1]); w.y = cvtpk(a[2], a[3]); w.z = cvtpk(b[0], b[1]); w.w = cvtpk(b[2], b[3]); return w; }
;     __device__ __forceinline__ static float sumsq8(const f32x4& a, const f32x4& b) { return ((a[0] * a[0] + a[1] * a[1]) + (a[2] * a[2] + a[3] * a[3])) + ((b[0] * b[0] + b[1] * b[1]) + (b[2] * b[2] + b[3] * b[3])); }
;     __device__ __forceinline__ static void row_atomic(sq_t* sq, int row, float s, int lane, int fq) { s += shx(s, lane, 16); s += shx(s, lane, 32); if (fq == 0) (void)__hip_atomic_fetch_add(sq + row, (sq_t)(s * 16777216.f), __ATOMIC_RELAXED, __HIP_MEMORY_SCOPE_AGENT); }
;     __device__ __forceinline__ void operator()(const f32x4 (&acc)[2][2][4][2], const Unit& u, int wr, int wc, int fr, int fq) const {
;     ...
;         } else if (mode == EM_WO || mode == EM_FF2) {
;             const bf16_t* hb = (const bf16_t*)(ws + WS_H); bf16_t* dst = (mode == EM_FF2 && flag) ? (bf16_t*)(ws + WS_MRG) : (bf16_t*)(ws + WS_H);
;             sq_t* sq = mode == EM_WO ? SQMID : (flag ? SQX + 4 * TCH : SQX);
; #pragma unroll
;             for (int ai = 0; ai < 2; ++ai)
; #pragma unroll
;                 for (int m = 0; m < 4; ++m) { const int row = row0 + ai * HALF + m * 16; float ss = 0.f;
; #pragma unroll
;                     for (int bj = 0; bj < 2; ++bj) { const size_t o = (size_t)row * 1024 + pn * 256 + bj * HALF + cw;
;                         const u32x4 xi = *(const u32x4*)(hb + o); f32x4 r0 = acc[ai][bj][m][0], r1 = acc[ai][bj][m][1];
;                         r0[0] += bflo(xi.x); r0[1] += bfhi(xi.x); r0[2] += bflo(xi.y); r0[3] += bfhi(xi.y); r1[0] += bflo(xi.z); r1[1] += bfhi(xi.z); r1[2] += bflo(xi.w); r1[3] += bfhi(xi.w);
;                         *(u32x4*)(dst + o) = pack8(r0, r1); ss += sumsq8(r0, r1); }
;                     row_atomic(sq, row, ss, lane, fq); }
.LBB0_1204:
	v_lshl_add_u32 v142, s3, 8, v144
	s_lshl_b32 s2, s2, 8
	s_ashr_i32 s3, s2, 31
	v_ashrrev_i32_e32 v143, 31, v142
	v_lshl_add_u64 v[140:141], s[2:3], 1, v[134:135]
	v_lshlrev_b64 v[152:153], 11, v[142:143]
	v_lshl_add_u64 v[156:157], v[140:141], 0, v[152:153]
	global_load_dwordx4 v[192:195], v[156:157], off
	global_load_dwordx4 v[196:199], v[156:157], off offset:256
	s_mov_b32 s98, 0x8000
	s_mov_b32 s99, 0
	v_lshl_add_u64 v[204:205], v[156:157], 0, s[98:99]
	global_load_dwordx4 v[200:203], v[204:205], off
	global_load_dwordx4 v[216:219], v[204:205], off offset:256
	s_mov_b32 s98, 0x10000
	s_mov_b32 s99, 0
	v_lshl_add_u64 v[204:205], v[156:157], 0, s[98:99]
	global_load_dwordx4 v[220:223], v[204:205], off
	global_load_dwordx4 v[224:227], v[204:205], off offset:256
	s_mov_b32 s98, 0x18000
	s_mov_b32 s99, 0
	v_lshl_add_u64 v[204:205], v[156:157], 0, s[98:99]
	global_load_dwordx4 v[228:231], v[204:205], off
	global_load_dwordx4 v[234:237], v[204:205], off offset:256
	s_mov_b32 s98, 0x40000
	s_mov_b32 s99, 0
	v_lshl_add_u64 v[204:205], v[156:157], 0, s[98:99]
	global_load_dwordx4 v[238:241], v[204:205], off
	global_load_dwordx4 v[242:245], v[204:205], off offset:256
	s_mov_b32 s98, 0x48000
	s_mov_b32 s99, 0
	v_lshl_add_u64 v[204:205], v[156:157], 0, s[98:99]
	global_load_dwordx4 v[246:249], v[204:205], off
	global_load_dwordx4 v[250:253], v[204:205], off offset:256
	s_waitcnt vmcnt(11)
	v_mov_b32_e32 v152, v192
	v_mov_b32_e32 v153, v193
	v_mov_b32_e32 v154, v194
	v_mov_b32_e32 v155, v195
	v_lshlrev_b32_e32 v158, 16, v152
	v_and_b32_e32 v159, 0xffff0000, v152
	v_lshlrev_b32_e32 v152, 16, v153
	v_and_b32_e32 v153, 0xffff0000, v153
	v_pk_add_f32 v[126:127], v[126:127], v[152:153]
	v_lshlrev_b32_e32 v152, 16, v154
	v_and_b32_e32 v153, 0xffff0000, v154
	v_pk_add_f32 v[152:153], v[120:121], v[152:153]
	v_lshlrev_b32_e32 v120, 16, v155
	v_and_b32_e32 v121, 0xffff0000, v155
	v_pk_add_f32 v[124:125], v[124:125], v[158:159]
	v_pk_add_f32 v[154:155], v[122:123], v[120:121]
	v_cvt_pk_bf16_f32 v120, v124, v125
	v_cvt_pk_bf16_f32 v121, v126, v127
	v_cvt_pk_bf16_f32 v122, v152, v153
	v_cvt_pk_bf16_f32 v123, v154, v155
	global_store_dwordx4 v[156:157], v[120:123], off
	s_nop 1
	v_pk_mul_f32 v[120:121], v[124:125], v[124:125]
	v_pk_mul_f32 v[122:123], v[126:127], v[126:127]
	v_pk_mul_f32 v[124:125], v[152:153], v[152:153]
	v_pk_mul_f32 v[126:127], v[154:155], v[154:155]
	s_waitcnt vmcnt(11)
	v_mov_b32_e32 v152, v196
	v_mov_b32_e32 v153, v197
	v_mov_b32_e32 v154, v198
	v_mov_b32_e32 v155, v199
	v_lshlrev_b32_e32 v158, 16, v152
	v_and_b32_e32 v159, 0xffff0000, v152
	v_lshlrev_b32_e32 v152, 16, v153
	v_and_b32_e32 v153, 0xffff0000, v153
	v_pk_add_f32 v[118:119], v[118:119], v[152:153]
	v_lshlrev_b32_e32 v152, 16, v154
	v_and_b32_e32 v153, 0xffff0000, v154
	v_pk_add_f32 v[152:153], v[112:113], v[152:153]
	v_lshlrev_b32_e32 v112, 16, v155
	v_and_b32_e32 v113, 0xffff0000, v155
	v_pk_add_f32 v[116:117], v[116:117], v[158:159]
	v_pk_add_f32 v[154:155], v[114:115], v[112:113]
	v_cvt_pk_bf16_f32 v112, v116, v117
	v_cvt_pk_bf16_f32 v113, v118, v119
	v_cvt_pk_bf16_f32 v114, v152, v153
	v_cvt_pk_bf16_f32 v115, v154, v155
	global_store_dwordx4 v[156:157], v[112:115], off offset:256
	s_nop 1
	v_pk_mul_f32 v[112:113], v[116:117], v[116:117]
	v_pk_mul_f32 v[114:115], v[118:119], v[118:119]
	v_add_f32_e32 v112, v112, v113
	v_add_f32_e32 v114, v114, v115
	v_pk_mul_f32 v[116:117], v[152:153], v[152:153]
	v_pk_mul_f32 v[118:119], v[154:155], v[154:155]
	v_add_f32_e32 v112, v112, v114
	v_add_f32_e32 v113, v126, v127
	v_add_f32_e32 v114, v124, v125
	v_add_f32_e32 v118, v118, v119
	v_add_f32_e32 v116, v116, v117
	v_add_f32_e32 v113, v114, v113
	v_add_f32_e32 v114, v122, v123
	v_add_f32_e32 v115, v120, v121
	v_add_f32_e32 v116, v116, v118
	v_add_f32_e32 v114, v115, v114
	v_add_f32_e32 v112, v112, v116
	v_add_f32_e32 v113, v114, v113
	v_add_f32_e32 v112, v113, v112
	ds_bpermute_b32 v113, v146, v112
	s_waitcnt lgkmcnt(0)
	v_add_f32_e32 v112, v112, v113
	ds_bpermute_b32 v113, v147, v112
	s_and_saveexec_b64 s[4:5], s[6:7]
	s_cbranch_execz .LBB0_1206
	s_waitcnt lgkmcnt(0)
	v_add_f32_e32 v112, v112, v113
	v_mul_f32_e32 v112, 0x4b800000, v112
	v_trunc_f32_e32 v112, v112
	v_mul_f32_e32 v113, 0x2f800000, v112
	v_floor_f32_e32 v113, v113
	v_fmac_f32_e32 v112, 0xcf800000, v113
	v_cvt_u32_f32_e32 v112, v112
	v_cvt_u32_f32_e32 v113, v113
	v_lshl_add_u64 v[114:115], v[142:143], 3, s[28:29]
	global_atomic_add_x2 v[114:115], v[112:113], off
;     __device__ __forceinline__ static u32x4 pack8(const f32x4& a, const f32x4& b) { u32x4 w; w.x = cvtpk(a[0], a[1]); w.y = cvtpk(a[2], a[3]); w.z = cvtpk(b[0], b[1]); w.w = cvtpk(b[2], b[3]); return w; }
;     __device__ __forceinline__ static float sumsq8(const f32x4& a, const f32x4& b) { return ((a[0] * a[0] + a[1] * a[1]) + (a[2] * a[2] + a[3] * a[3])) + ((b[0] * b[0] + b[1] * b[1]) + (b[2] * b[2] + b[3] * b[3])); }
;     __device__ __forceinline__ static void row_atomic(sq_t* sq, int row, float s, int lane, int fq) { s += shx(s, lane, 16); s += shx(s, lane, 32); if (fq == 0) (void)__hip_atomic_fetch_add(sq + row, (sq_t)(s * 16777216.f), __ATOMIC_RELAXED, __HIP_MEMORY_SCOPE_AGENT); }
;     __device__ __forceinline__ void operator()(const f32x4 (&acc)[2][2][4][2], const Unit& u, int wr, int wc, int fr, int fq) const {
;     ...
;         } else if (mode == EM_WO || mode == EM_FF2) {
;             const bf16_t* hb = (const bf16_t*)(ws + WS_H); bf16_t* dst = (mode == EM_FF2 && flag) ? (bf16_t*)(ws + WS_MRG) : (bf16_t*)(ws + WS_H);
;             sq_t* sq = mode == EM_WO ? SQMID : (flag ? SQX + 4 * TCH : SQX);
; #pragma unroll
;             for (int ai = 0; ai < 2; ++ai)
; #pragma unroll
;                 for (int m = 0; m < 4; ++m) { const int row = row0 + ai * HALF + m * 16; float ss = 0.f;
; #pragma unroll
;                     for (int bj = 0; bj < 2; ++bj) { const size_t o = (size_t)row * 1024 + pn * 256 + bj * HALF + cw;
;                         const u32x4 xi = *(const u32x4*)(hb + o); f32x4 r0 = acc[ai][bj][m][0], r1 = acc[ai][bj][m][1];
;                         r0[0] += bflo(xi.x); r0[1] += bfhi(xi.x); r0[2] += bflo(xi.y); r0[3] += bfhi(xi.y); r1[0] += bflo(xi.z); r1[1] += bfhi(xi.z); r1[2] += bflo(xi.w); r1[3] += bfhi(xi.w);
;                         *(u32x4*)(dst + o) = pack8(r0, r1); ss += sumsq8(r0, r1); }
;                     row_atomic(sq, row, ss, lane, fq); }
.LBB0_1206:
	s_or_b64 exec, exec, s[4:5]
	v_or_b32_e32 v112, 16, v142
	s_waitcnt lgkmcnt(0)
	v_ashrrev_i32_e32 v113, 31, v112
	v_lshlrev_b64 v[114:115], 11, v[112:113]
	v_lshl_add_u64 v[118:119], v[140:141], 0, v[114:115]
	s_waitcnt vmcnt(11)
	v_mov_b32_e32 v114, v200
	v_mov_b32_e32 v115, v201
	v_mov_b32_e32 v116, v202
	v_mov_b32_e32 v117, v203
	v_lshlrev_b32_e32 v120, 16, v114
	v_and_b32_e32 v121, 0xffff0000, v114
	v_lshlrev_b32_e32 v114, 16, v115
	v_and_b32_e32 v115, 0xffff0000, v115
	v_pk_add_f32 v[110:111], v[110:111], v[114:115]
	v_lshlrev_b32_e32 v114, 16, v116
	v_and_b32_e32 v115, 0xffff0000, v116
	v_pk_add_f32 v[114:115], v[104:105], v[114:115]
	v_lshlrev_b32_e32 v104, 16, v117
	v_and_b32_e32 v105, 0xffff0000, v117
	v_pk_add_f32 v[108:109], v[108:109], v[120:121]
	v_pk_add_f32 v[116:117], v[106:107], v[104:105]
	v_cvt_pk_bf16_f32 v104, v108, v109
	v_cvt_pk_bf16_f32 v105, v110, v111
	v_cvt_pk_bf16_f32 v106, v114, v115
	v_cvt_pk_bf16_f32 v107, v116, v117
	global_store_dwordx4 v[118:119], v[104:107], off
	s_nop 1
	v_pk_mul_f32 v[104:105], v[108:109], v[108:109]
	v_pk_mul_f32 v[106:107], v[110:111], v[110:111]
	v_pk_mul_f32 v[108:109], v[114:115], v[114:115]
	v_pk_mul_f32 v[110:111], v[116:117], v[116:117]
	s_waitcnt vmcnt(11)
	v_mov_b32_e32 v114, v216
	v_mov_b32_e32 v115, v217
	v_mov_b32_e32 v116, v218
	v_mov_b32_e32 v117, v219
	s_mov_b32 s98, 0x50000
	s_mov_b32 s99, 0
	v_lshl_add_u64 v[204:205], v[156:157], 0, s[98:99]
	global_load_dwordx4 v[192:195], v[204:205], off
	global_load_dwordx4 v[196:199], v[204:205], off offset:256
	s_mov_b32 s98, 0x58000
	s_mov_b32 s99, 0
	v_lshl_add_u64 v[204:205], v[156:157], 0, s[98:99]
	global_load_dwordx4 v[200:203], v[204:205], off
	global_load_dwordx4 v[216:219], v[204:205], off offset:256
	v_lshlrev_b32_e32 v120, 16, v114
	v_and_b32_e32 v121, 0xffff0000, v114
	v_lshlrev_b32_e32 v114, 16, v115
	v_and_b32_e32 v115, 0xffff0000, v115
	v_pk_add_f32 v[102:103], v[102:103], v[114:115]
	v_lshlrev_b32_e32 v114, 16, v116
	v_and_b32_e32 v115, 0xffff0000, v116
	v_pk_add_f32 v[114:115], v[96:97], v[114:115]
	v_lshlrev_b32_e32 v96, 16, v117
	v_and_b32_e32 v97, 0xffff0000, v117
	v_pk_add_f32 v[100:101], v[100:101], v[120:121]
	v_pk_add_f32 v[116:117], v[98:99], v[96:97]
	v_cvt_pk_bf16_f32 v96, v100, v101
	v_cvt_pk_bf16_f32 v97, v102, v103
	v_cvt_pk_bf16_f32 v98, v114, v115
	v_cvt_pk_bf16_f32 v99, v116, v117
	global_store_dwordx4 v[118:119], v[96:99], off offset:256
	s_nop 1
	v_pk_mul_f32 v[96:97], v[100:101], v[100:101]
	v_pk_mul_f32 v[98:99], v[102:103], v[102:103]
	v_add_f32_e32 v96, v96, v97
	v_add_f32_e32 v98, v98, v99
	v_pk_mul_f32 v[100:101], v[114:115], v[114:115]
	v_pk_mul_f32 v[102:103], v[116:117], v[116:117]
	v_add_f32_e32 v96, v96, v98
	v_add_f32_e32 v97, v110, v111
	v_add_f32_e32 v98, v108, v109
	v_add_f32_e32 v102, v102, v103
	v_add_f32_e32 v100, v100, v101
	v_add_f32_e32 v97, v98, v97
	v_add_f32_e32 v98, v106, v107
	v_add_f32_e32 v99, v104, v105
	v_add_f32_e32 v100, v100, v102
	v_add_f32_e32 v98, v99, v98
	v_add_f32_e32 v96, v96, v100
	v_add_f32_e32 v97, v98, v97
	v_add_f32_e32 v96, v97, v96
	ds_bpermute_b32 v97, v146, v96
	s_waitcnt lgkmcnt(0)
	v_add_f32_e32 v96, v96, v97
	ds_bpermute_b32 v97, v147, v96
	s_and_saveexec_b64 s[4:5], s[6:7]
	s_cbranch_execz .LBB0_1208
	s_waitcnt lgkmcnt(0)
	v_add_f32_e32 v96, v96, v97
	v_mul_f32_e32 v96, 0x4b800000, v96
	v_trunc_f32_e32 v96, v96
	v_mul_f32_e32 v97, 0x2f800000, v96
	v_floor_f32_e32 v97, v97
	v_fmac_f32_e32 v96, 0xcf800000, v97
	v_cvt_u32_f32_e32 v96, v96
	v_cvt_u32_f32_e32 v97, v97
	v_lshl_add_u64 v[98:99], v[112:113], 3, s[28:29]
	global_atomic_add_x2 v[98:99], v[96:97], off
.LBB0_1208:
	s_or_b64 exec, exec, s[4:5]
	v_or_b32_e32 v96, 32, v142
	s_waitcnt lgkmcnt(0)
	v_ashrrev_i32_e32 v97, 31, v96
	v_lshlrev_b64 v[98:99], 11, v[96:97]
	v_lshl_add_u64 v[102:103], v[140:141], 0, v[98:99]
	s_waitcnt vmcnt(15)
	v_mov_b32_e32 v98, v220
	v_mov_b32_e32 v99, v221
	v_mov_b32_e32 v100, v222
	v_mov_b32_e32 v101, v223
	v_lshlrev_b32_e32 v104, 16, v98
	v_and_b32_e32 v105, 0xffff0000, v98
	v_lshlrev_b32_e32 v98, 16, v99
	v_and_b32_e32 v99, 0xffff0000, v99
	v_pk_add_f32 v[94:95], v[94:95], v[98:99]
	v_lshlrev_b32_e32 v98, 16, v100
	v_and_b32_e32 v99, 0xffff0000, v100
	v_pk_add_f32 v[98:99], v[88:89], v[98:99]
	v_lshlrev_b32_e32 v88, 16, v101
	v_and_b32_e32 v89, 0xffff0000, v101
	v_pk_add_f32 v[92:93], v[92:93], v[104:105]
	v_pk_add_f32 v[100:101], v[90:91], v[88:89]
	v_cvt_pk_bf16_f32 v88, v92, v93
	v_cvt_pk_bf16_f32 v89, v94, v95
	v_cvt_pk_bf16_f32 v90, v98, v99
	v_cvt_pk_bf16_f32 v91, v100, v101
	global_store_dwordx4 v[102:103], v[88:91], off
	s_nop 1
	v_pk_mul_f32 v[88:89], v[92:93], v[92:93]
	v_pk_mul_f32 v[90:91], v[94:95], v[94:95]
	v_pk_mul_f32 v[92:93], v[98:99], v[98:99]
	v_pk_mul_f32 v[94:95], v[100:101], v[100:101]
	s_waitcnt vmcnt(15)
	v_mov_b32_e32 v98, v224
	v_mov_b32_e32 v99, v225
	v_mov_b32_e32 v100, v226
	v_mov_b32_e32 v101, v227
	v_lshlrev_b32_e32 v104, 16, v98
	v_and_b32_e32 v105, 0xffff0000, v98
	v_lshlrev_b32_e32 v98, 16, v99
	v_and_b32_e32 v99, 0xffff0000, v99
	v_pk_add_f32 v[86:87], v[86:87], v[98:99]
	v_lshlrev_b32_e32 v98, 16, v100
	v_and_b32_e32 v99, 0xffff0000, v100
	v_pk_add_f32 v[98:99], v[80:81], v[98:99]
	v_lshlrev_b32_e32 v80, 16, v101
	v_and_b32_e32 v81, 0xffff0000, v101
	v_pk_add_f32 v[84:85], v[84:85], v[104:105]
	v_pk_add_f32 v[100:101], v[82:83], v[80:81]
	v_cvt_pk_bf16_f32 v80, v84, v85
	v_cvt_pk_bf16_f32 v81, v86, v87
	v_cvt_pk_bf16_f32 v82, v98, v99
	v_cvt_pk_bf16_f32 v83, v100, v101
	global_store_dwordx4 v[102:103], v[80:83], off offset:256
	s_nop 1
	v_pk_mul_f32 v[80:81], v[84:85], v[84:85]
	v_pk_mul_f32 v[82:83], v[86:87], v[86:87]
	v_add_f32_e32 v80, v80, v81
	v_add_f32_e32 v82, v82, v83
	v_pk_mul_f32 v[84:85], v[98:99], v[98:99]
	v_pk_mul_f32 v[86:87], v[100:101], v[100:101]
	v_add_f32_e32 v80, v80, v82
	v_add_f32_e32 v81, v94, v95
	v_add_f32_e32 v82, v92, v93
	v_add_f32_e32 v86, v86, v87
	v_add_f32_e32 v84, v84, v85
	v_add_f32_e32 v81, v82, v81
	v_add_f32_e32 v82, v90, v91
	v_add_f32_e32 v83, v88, v89
	v_add_f32_e32 v84, v84, v86
	v_add_f32_e32 v82, v83, v82
	v_add_f32_e32 v80, v80, v84
	v_add_f32_e32 v81, v82, v81
	v_add_f32_e32 v80, v81, v80
	ds_bpermute_b32 v81, v146, v80
	s_waitcnt lgkmcnt(0)
	v_add_f32_e32 v80, v80, v81
	ds_bpermute_b32 v81, v147, v80
	s_and_saveexec_b64 s[4:5], s[6:7]
	s_cbranch_execz .LBB0_1210
	s_waitcnt lgkmcnt(0)
	v_add_f32_e32 v80, v80, v81
	v_mul_f32_e32 v80, 0x4b800000, v80
	v_trunc_f32_e32 v80, v80
	v_mul_f32_e32 v81, 0x2f800000, v80
	v_floor_f32_e32 v81, v81
	v_fmac_f32_e32 v80, 0xcf800000, v81
	v_cvt_u32_f32_e32 v80, v80
	v_cvt_u32_f32_e32 v81, v81
	v_lshl_add_u64 v[82:83], v[96:97], 3, s[28:29]
	global_atomic_add_x2 v[82:83], v[80:81], off
;     __device__ __forceinline__ static u32x4 pack8(const f32x4& a, const f32x4& b) { u32x4 w; w.x = cvtpk(a[0], a[1]); w.y = cvtpk(a[2], a[3]); w.z = cvtpk(b[0], b[1]); w.w = cvtpk(b[2], b[3]); return w; }
;     __device__ __forceinline__ static float sumsq8(const f32x4& a, const f32x4& b) { return ((a[0] * a[0] + a[1] * a[1]) + (a[2] * a[2] + a[3] * a[3])) + ((b[0] * b[0] + b[1] * b[1]) + (b[2] * b[2] + b[3] * b[3])); }
;     __device__ __forceinline__ static void row_atomic(sq_t* sq, int row, float s, int lane, int fq) { s += shx(s, lane, 16); s += shx(s, lane, 32); if (fq == 0) (void)__hip_atomic_fetch_add(sq + row, (sq_t)(s * 16777216.f), __ATOMIC_RELAXED, __HIP_MEMORY_SCOPE_AGENT); }
;     __device__ __forceinline__ void operator()(const f32x4 (&acc)[2][2][4][2], const Unit& u, int wr, int wc, int fr, int fq) const {
;     ...
;         } else if (mode == EM_WO || mode == EM_FF2) {
;             const bf16_t* hb = (const bf16_t*)(ws + WS_H); bf16_t* dst = (mode == EM_FF2 && flag) ? (bf16_t*)(ws + WS_MRG) : (bf16_t*)(ws + WS_H);
;             sq_t* sq = mode == EM_WO ? SQMID : (flag ? SQX + 4 * TCH : SQX);
; #pragma unroll
;             for (int ai = 0; ai < 2; ++ai)
; #pragma unroll
;                 for (int m = 0; m < 4; ++m) { const int row = row0 + ai * HALF + m * 16; float ss = 0.f;
; #pragma unroll
;                     for (int bj = 0; bj < 2; ++bj) { const size_t o = (size_t)row * 1024 + pn * 256 + bj * HALF + cw;
;                         const u32x4 xi = *(const u32x4*)(hb + o); f32x4 r0 = acc[ai][bj][m][0], r1 = acc[ai][bj][m][1];
;                         r0[0] += bflo(xi.x); r0[1] += bfhi(xi.x); r0[2] += bflo(xi.y); r0[3] += bfhi(xi.y); r1[0] += bflo(xi.z); r1[1] += bfhi(xi.z); r1[2] += bflo(xi.w); r1[3] += bfhi(xi.w);
;                         *(u32x4*)(dst + o) = pack8(r0, r1); ss += sumsq8(r0, r1); }
;                     row_atomic(sq, row, ss, lane, fq); }
.LBB0_1210:
	s_or_b64 exec, exec, s[4:5]
	v_or_b32_e32 v80, 48, v142
	s_waitcnt lgkmcnt(0)
	v_ashrrev_i32_e32 v81, 31, v80
	v_lshlrev_b64 v[82:83], 11, v[80:81]
	v_lshl_add_u64 v[86:87], v[140:141], 0, v[82:83]
	s_waitcnt vmcnt(15)
	v_mov_b32_e32 v82, v228
	v_mov_b32_e32 v83, v229
	v_mov_b32_e32 v84, v230
	v_mov_b32_e32 v85, v231
	v_lshlrev_b32_e32 v88, 16, v82
	v_and_b32_e32 v89, 0xffff0000, v82
	v_lshlrev_b32_e32 v82, 16, v83
	v_and_b32_e32 v83, 0xffff0000, v83
	v_pk_add_f32 v[78:79], v[78:79], v[82:83]
	v_lshlrev_b32_e32 v82, 16, v84
	v_and_b32_e32 v83, 0xffff0000, v84
	v_pk_add_f32 v[82:83], v[72:73], v[82:83]
	v_lshlrev_b32_e32 v72, 16, v85
	v_and_b32_e32 v73, 0xffff0000, v85
	v_pk_add_f32 v[76:77], v[76:77], v[88:89]
	v_pk_add_f32 v[84:85], v[74:75], v[72:73]
	v_cvt_pk_bf16_f32 v72, v76, v77
	v_cvt_pk_bf16_f32 v73, v78, v79
	v_cvt_pk_bf16_f32 v74, v82, v83
	v_cvt_pk_bf16_f32 v75, v84, v85
	global_store_dwordx4 v[86:87], v[72:75], off
	s_nop 1
	v_pk_mul_f32 v[72:73], v[76:77], v[76:77]
	v_pk_mul_f32 v[74:75], v[78:79], v[78:79]
	v_pk_mul_f32 v[76:77], v[82:83], v[82:83]
	v_pk_mul_f32 v[78:79], v[84:85], v[84:85]
	s_waitcnt vmcnt(15)
	v_mov_b32_e32 v82, v234
	v_mov_b32_e32 v83, v235
	v_mov_b32_e32 v84, v236
	v_mov_b32_e32 v85, v237
	v_lshlrev_b32_e32 v88, 16, v82
	v_and_b32_e32 v89, 0xffff0000, v82
	v_lshlrev_b32_e32 v82, 16, v83
	v_and_b32_e32 v83, 0xffff0000, v83
	v_pk_add_f32 v[70:71], v[70:71], v[82:83]
	v_lshlrev_b32_e32 v82, 16, v84
	v_and_b32_e32 v83, 0xffff0000, v84
	v_pk_add_f32 v[82:83], v[64:65], v[82:83]
	v_lshlrev_b32_e32 v64, 16, v85
	v_and_b32_e32 v65, 0xffff0000, v85
	v_pk_add_f32 v[68:69], v[68:69], v[88:89]
	v_pk_add_f32 v[84:85], v[66:67], v[64:65]
	v_cvt_pk_bf16_f32 v64, v68, v69
	v_cvt_pk_bf16_f32 v65, v70, v71
	v_cvt_pk_bf16_f32 v66, v82, v83
	v_cvt_pk_bf16_f32 v67, v84, v85
	global_store_dwordx4 v[86:87], v[64:67], off offset:256
	s_nop 1
	v_pk_mul_f32 v[64:65], v[68:69], v[68:69]
	v_pk_mul_f32 v[66:67], v[70:71], v[70:71]
	v_add_f32_e32 v64, v64, v65
	v_add_f32_e32 v66, v66, v67
	v_pk_mul_f32 v[68:69], v[82:83], v[82:83]
	v_pk_mul_f32 v[70:71], v[84:85], v[84:85]
	v_add_f32_e32 v64, v64, v66
	v_add_f32_e32 v65, v78, v79
	v_add_f32_e32 v66, v76, v77
	v_add_f32_e32 v70, v70, v71
	v_add_f32_e32 v68, v68, v69
	v_add_f32_e32 v65, v66, v65
	v_add_f32_e32 v66, v74, v75
	v_add_f32_e32 v67, v72, v73
	v_add_f32_e32 v68, v68, v70
	v_add_f32_e32 v66, v67, v66
	v_add_f32_e32 v64, v64, v68
	v_add_f32_e32 v65, v66, v65
	v_add_f32_e32 v64, v65, v64
	ds_bpermute_b32 v65, v146, v64
	s_waitcnt lgkmcnt(0)
	v_add_f32_e32 v64, v64, v65
	ds_bpermute_b32 v65, v147, v64
	s_and_saveexec_b64 s[4:5], s[6:7]
	s_cbranch_execz .LBB0_1212
	s_waitcnt lgkmcnt(0)
	v_add_f32_e32 v64, v64, v65
	v_mul_f32_e32 v64, 0x4b800000, v64
	v_trunc_f32_e32 v64, v64
	v_mul_f32_e32 v65, 0x2f800000, v64
	v_floor_f32_e32 v65, v65
	v_fmac_f32_e32 v64, 0xcf800000, v65
	v_cvt_u32_f32_e32 v64, v64
	v_cvt_u32_f32_e32 v65, v65
	v_lshl_add_u64 v[66:67], v[80:81], 3, s[28:29]
	global_atomic_add_x2 v[66:67], v[64:65], off
.LBB0_1212:
	s_or_b64 exec, exec, s[4:5]
	v_add_u32_e32 v64, 0x80, v142
	s_waitcnt lgkmcnt(0)
	v_ashrrev_i32_e32 v65, 31, v64
	v_lshlrev_b64 v[66:67], 11, v[64:65]
	v_lshl_add_u64 v[70:71], v[140:141], 0, v[66:67]
	s_waitcnt vmcnt(15)
	v_mov_b32_e32 v66, v238
	v_mov_b32_e32 v67, v239
	v_mov_b32_e32 v68, v240
	v_mov_b32_e32 v69, v241
	v_lshlrev_b32_e32 v72, 16, v66
	v_and_b32_e32 v73, 0xffff0000, v66
	v_lshlrev_b32_e32 v66, 16, v67
	v_and_b32_e32 v67, 0xffff0000, v67
	v_pk_add_f32 v[62:63], v[62:63], v[66:67]
	v_lshlrev_b32_e32 v66, 16, v68
	v_and_b32_e32 v67, 0xffff0000, v68
	v_pk_add_f32 v[66:67], v[56:57], v[66:67]
	v_lshlrev_b32_e32 v56, 16, v69
	v_and_b32_e32 v57, 0xffff0000, v69
	v_pk_add_f32 v[60:61], v[60:61], v[72:73]
	v_pk_add_f32 v[68:69], v[58:59], v[56:57]
	v_cvt_pk_bf16_f32 v56, v60, v61
	v_cvt_pk_bf16_f32 v57, v62, v63
	v_cvt_pk_bf16_f32 v58, v66, v67
	v_cvt_pk_bf16_f32 v59, v68, v69
	global_store_dwordx4 v[70:71], v[56:59], off
	s_nop 1
	v_pk_mul_f32 v[56:57], v[60:61], v[60:61]
	v_pk_mul_f32 v[58:59], v[62:63], v[62:63]
	v_pk_mul_f32 v[60:61], v[66:67], v[66:67]
	v_pk_mul_f32 v[62:63], v[68:69], v[68:69]
	s_waitcnt vmcnt(15)
	v_mov_b32_e32 v66, v242
	v_mov_b32_e32 v67, v243
	v_mov_b32_e32 v68, v244
	v_mov_b32_e32 v69, v245
	v_lshlrev_b32_e32 v72, 16, v66
	v_and_b32_e32 v73, 0xffff0000, v66
	v_lshlrev_b32_e32 v66, 16, v67
	v_and_b32_e32 v67, 0xffff0000, v67
	v_pk_add_f32 v[54:55], v[54:55], v[66:67]
	v_lshlrev_b32_e32 v66, 16, v68
	v_and_b32_e32 v67, 0xffff0000, v68
	v_pk_add_f32 v[66:67], v[48:49], v[66:67]
	v_lshlrev_b32_e32 v48, 16, v69
	v_and_b32_e32 v49, 0xffff0000, v69
	v_pk_add_f32 v[52:53], v[52:53], v[72:73]
	v_pk_add_f32 v[68:69], v[50:51], v[48:49]
	v_cvt_pk_bf16_f32 v48, v52, v53
	v_cvt_pk_bf16_f32 v49, v54, v55
	v_cvt_pk_bf16_f32 v50, v66, v67
	v_cvt_pk_bf16_f32 v51, v68, v69
	global_store_dwordx4 v[70:71], v[48:51], off offset:256
	s_nop 1
	v_pk_mul_f32 v[48:49], v[52:53], v[52:53]
	v_pk_mul_f32 v[50:51], v[54:55], v[54:55]
	v_add_f32_e32 v48, v48, v49
	v_add_f32_e32 v50, v50, v51
	v_pk_mul_f32 v[52:53], v[66:67], v[66:67]
	v_pk_mul_f32 v[54:55], v[68:69], v[68:69]
	v_add_f32_e32 v48, v48, v50
	v_add_f32_e32 v49, v62, v63
	v_add_f32_e32 v50, v60, v61
	v_add_f32_e32 v54, v54, v55
	v_add_f32_e32 v52, v52, v53
	v_add_f32_e32 v49, v50, v49
	v_add_f32_e32 v50, v58, v59
	v_add_f32_e32 v51, v56, v57
	v_add_f32_e32 v52, v52, v54
	v_add_f32_e32 v50, v51, v50
	v_add_f32_e32 v48, v48, v52
	v_add_f32_e32 v49, v50, v49
	v_add_f32_e32 v48, v49, v48
	ds_bpermute_b32 v49, v146, v48
	s_waitcnt lgkmcnt(0)
	v_add_f32_e32 v48, v48, v49
	ds_bpermute_b32 v49, v147, v48
	s_and_saveexec_b64 s[4:5], s[6:7]
	s_cbranch_execz .LBB0_1214
	s_waitcnt lgkmcnt(0)
	v_add_f32_e32 v48, v48, v49
	v_mul_f32_e32 v48, 0x4b800000, v48
	v_trunc_f32_e32 v48, v48
	v_mul_f32_e32 v49, 0x2f800000, v48
	v_floor_f32_e32 v49, v49
	v_fmac_f32_e32 v48, 0xcf800000, v49
	v_cvt_u32_f32_e32 v48, v48
	v_cvt_u32_f32_e32 v49, v49
	v_lshl_add_u64 v[50:51], v[64:65], 3, s[28:29]
	global_atomic_add_x2 v[50:51], v[48:49], off
;     __device__ __forceinline__ static u32x4 pack8(const f32x4& a, const f32x4& b) { u32x4 w; w.x = cvtpk(a[0], a[1]); w.y = cvtpk(a[2], a[3]); w.z = cvtpk(b[0], b[1]); w.w = cvtpk(b[2], b[3]); return w; }
;     __device__ __forceinline__ static float sumsq8(const f32x4& a, const f32x4& b) { return ((a[0] * a[0] + a[1] * a[1]) + (a[2] * a[2] + a[3] * a[3])) + ((b[0] * b[0] + b[1] * b[1]) + (b[2] * b[2] + b[3] * b[3])); }
;     __device__ __forceinline__ static void row_atomic(sq_t* sq, int row, float s, int lane, int fq) { s += shx(s, lane, 16); s += shx(s, lane, 32); if (fq == 0) (void)__hip_atomic_fetch_add(sq + row, (sq_t)(s * 16777216.f), __ATOMIC_RELAXED, __HIP_MEMORY_SCOPE_AGENT); }
;     __device__ __forceinline__ void operator()(const f32x4 (&acc)[2][2][4][2], const Unit& u, int wr, int wc, int fr, int fq) const {
;     ...
;         } else if (mode == EM_WO || mode == EM_FF2) {
;             const bf16_t* hb = (const bf16_t*)(ws + WS_H); bf16_t* dst = (mode == EM_FF2 && flag) ? (bf16_t*)(ws + WS_MRG) : (bf16_t*)(ws + WS_H);
;             sq_t* sq = mode == EM_WO ? SQMID : (flag ? SQX + 4 * TCH : SQX);
; #pragma unroll
;             for (int ai = 0; ai < 2; ++ai)
; #pragma unroll
;                 for (int m = 0; m < 4; ++m) { const int row = row0 + ai * HALF + m * 16; float ss = 0.f;
; #pragma unroll
;                     for (int bj = 0; bj < 2; ++bj) { const size_t o = (size_t)row * 1024 + pn * 256 + bj * HALF + cw;
;                         const u32x4 xi = *(const u32x4*)(hb + o); f32x4 r0 = acc[ai][bj][m][0], r1 = acc[ai][bj][m][1];
;                         r0[0] += bflo(xi.x); r0[1] += bfhi(xi.x); r0[2] += bflo(xi.y); r0[3] += bfhi(xi.y); r1[0] += bflo(xi.z); r1[1] += bfhi(xi.z); r1[2] += bflo(xi.w); r1[3] += bfhi(xi.w);
;                         *(u32x4*)(dst + o) = pack8(r0, r1); ss += sumsq8(r0, r1); }
;                     row_atomic(sq, row, ss, lane, fq); }
.LBB0_1214:
	s_or_b64 exec, exec, s[4:5]
	v_add_u32_e32 v48, 0x90, v142
	s_waitcnt lgkmcnt(0)
	v_ashrrev_i32_e32 v49, 31, v48
	v_lshlrev_b64 v[50:51], 11, v[48:49]
	v_lshl_add_u64 v[54:55], v[140:141], 0, v[50:51]
	s_waitcnt vmcnt(15)
	v_mov_b32_e32 v50, v246
	v_mov_b32_e32 v51, v247
	v_mov_b32_e32 v52, v248
	v_mov_b32_e32 v53, v249
	v_lshlrev_b32_e32 v56, 16, v50
	v_and_b32_e32 v57, 0xffff0000, v50
	v_lshlrev_b32_e32 v50, 16, v51
	v_and_b32_e32 v51, 0xffff0000, v51
	v_pk_add_f32 v[46:47], v[46:47], v[50:51]
	v_lshlrev_b32_e32 v50, 16, v52
	v_and_b32_e32 v51, 0xffff0000, v52
	v_pk_add_f32 v[50:51], v[40:41], v[50:51]
	v_lshlrev_b32_e32 v40, 16, v53
	v_and_b32_e32 v41, 0xffff0000, v53
	v_pk_add_f32 v[44:45], v[44:45], v[56:57]
	v_pk_add_f32 v[52:53], v[42:43], v[40:41]
	v_cvt_pk_bf16_f32 v40, v44, v45
	v_cvt_pk_bf16_f32 v41, v46, v47
	v_cvt_pk_bf16_f32 v42, v50, v51
	v_cvt_pk_bf16_f32 v43, v52, v53
	global_store_dwordx4 v[54:55], v[40:43], off
	s_nop 1
	v_pk_mul_f32 v[40:41], v[44:45], v[44:45]
	v_pk_mul_f32 v[42:43], v[46:47], v[46:47]
	v_pk_mul_f32 v[44:45], v[50:51], v[50:51]
	v_pk_mul_f32 v[46:47], v[52:53], v[52:53]
	s_waitcnt vmcnt(15)
	v_mov_b32_e32 v50, v250
	v_mov_b32_e32 v51, v251
	v_mov_b32_e32 v52, v252
	v_mov_b32_e32 v53, v253
	v_lshlrev_b32_e32 v56, 16, v50
	v_and_b32_e32 v57, 0xffff0000, v50
	v_lshlrev_b32_e32 v50, 16, v51
	v_and_b32_e32 v51, 0xffff0000, v51
	v_pk_add_f32 v[38:39], v[38:39], v[50:51]
	v_lshlrev_b32_e32 v50, 16, v52
	v_and_b32_e32 v51, 0xffff0000, v52
	v_pk_add_f32 v[50:51], v[32:33], v[50:51]
	v_lshlrev_b32_e32 v32, 16, v53
	v_and_b32_e32 v33, 0xffff0000, v53
	v_pk_add_f32 v[36:37], v[36:37], v[56:57]
	v_pk_add_f32 v[52:53], v[34:35], v[32:33]
	v_cvt_pk_bf16_f32 v32, v36, v37
	v_cvt_pk_bf16_f32 v33, v38, v39
	v_cvt_pk_bf16_f32 v34, v50, v51
	v_cvt_pk_bf16_f32 v35, v52, v53
	global_store_dwordx4 v[54:55], v[32:35], off offset:256
	s_nop 1
	v_pk_mul_f32 v[32:33], v[36:37], v[36:37]
	v_pk_mul_f32 v[34:35], v[38:39], v[38:39]
	v_add_f32_e32 v32, v32, v33
	v_add_f32_e32 v34, v34, v35
	v_pk_mul_f32 v[36:37], v[50:51], v[50:51]
	v_pk_mul_f32 v[38:39], v[52:53], v[52:53]
	v_add_f32_e32 v32, v32, v34
	v_add_f32_e32 v33, v46, v47
	v_add_f32_e32 v34, v44, v45
	v_add_f32_e32 v38, v38, v39
	v_add_f32_e32 v36, v36, v37
	v_add_f32_e32 v33, v34, v33
	v_add_f32_e32 v34, v42, v43
	v_add_f32_e32 v35, v40, v41
	v_add_f32_e32 v36, v36, v38
	v_add_f32_e32 v34, v35, v34
	v_add_f32_e32 v32, v32, v36
	v_add_f32_e32 v33, v34, v33
	v_add_f32_e32 v32, v33, v32
	ds_bpermute_b32 v33, v146, v32
	s_waitcnt lgkmcnt(0)
	v_add_f32_e32 v32, v32, v33
	ds_bpermute_b32 v33, v147, v32
	s_and_saveexec_b64 s[4:5], s[6:7]
	s_cbranch_execz .LBB0_1216
	s_waitcnt lgkmcnt(0)
	v_add_f32_e32 v32, v32, v33
	v_mul_f32_e32 v32, 0x4b800000, v32
	v_trunc_f32_e32 v32, v32
	v_mul_f32_e32 v33, 0x2f800000, v32
	v_floor_f32_e32 v33, v33
	v_fmac_f32_e32 v32, 0xcf800000, v33
	v_cvt_u32_f32_e32 v32, v32
	v_cvt_u32_f32_e32 v33, v33
	v_lshl_add_u64 v[34:35], v[48:49], 3, s[28:29]
	global_atomic_add_x2 v[34:35], v[32:33], off
;     __device__ __forceinline__ static u32x4 pack8(const f32x4& a, const f32x4& b) { u32x4 w; w.x = cvtpk(a[0], a[1]); w.y = cvtpk(a[2], a[3]); w.z = cvtpk(b[0], b[1]); w.w = cvtpk(b[2], b[3]); return w; }
;     __device__ __forceinline__ static float sumsq8(const f32x4& a, const f32x4& b) { return ((a[0] * a[0] + a[1] * a[1]) + (a[2] * a[2] + a[3] * a[3])) + ((b[0] * b[0] + b[1] * b[1]) + (b[2] * b[2] + b[3] * b[3])); }
;     __device__ __forceinline__ static void row_atomic(sq_t* sq, int row, float s, int lane, int fq) { s += shx(s, lane, 16); s += shx(s, lane, 32); if (fq == 0) (void)__hip_atomic_fetch_add(sq + row, (sq_t)(s * 16777216.f), __ATOMIC_RELAXED, __HIP_MEMORY_SCOPE_AGENT); }
;     __device__ __forceinline__ void operator()(const f32x4 (&acc)[2][2][4][2], const Unit& u, int wr, int wc, int fr, int fq) const {
;     ...
;         } else if (mode == EM_WO || mode == EM_FF2) {
;             const bf16_t* hb = (const bf16_t*)(ws + WS_H); bf16_t* dst = (mode == EM_FF2 && flag) ? (bf16_t*)(ws + WS_MRG) : (bf16_t*)(ws + WS_H);
;             sq_t* sq = mode == EM_WO ? SQMID : (flag ? SQX + 4 * TCH : SQX);
; #pragma unroll
;             for (int ai = 0; ai < 2; ++ai)
; #pragma unroll
;                 for (int m = 0; m < 4; ++m) { const int row = row0 + ai * HALF + m * 16; float ss = 0.f;
; #pragma unroll
;                     for (int bj = 0; bj < 2; ++bj) { const size_t o = (size_t)row * 1024 + pn * 256 + bj * HALF + cw;
;                         const u32x4 xi = *(const u32x4*)(hb + o); f32x4 r0 = acc[ai][bj][m][0], r1 = acc[ai][bj][m][1];
;                         r0[0] += bflo(xi.x); r0[1] += bfhi(xi.x); r0[2] += bflo(xi.y); r0[3] += bfhi(xi.y); r1[0] += bflo(xi.z); r1[1] += bfhi(xi.z); r1[2] += bflo(xi.w); r1[3] += bfhi(xi.w);
;                         *(u32x4*)(dst + o) = pack8(r0, r1); ss += sumsq8(r0, r1); }
;                     row_atomic(sq, row, ss, lane, fq); }
.LBB0_1216:
	s_or_b64 exec, exec, s[4:5]
	v_add_u32_e32 v32, 0xa0, v142
	s_waitcnt lgkmcnt(0)
	v_ashrrev_i32_e32 v33, 31, v32
	v_lshlrev_b64 v[34:35], 11, v[32:33]
	v_lshl_add_u64 v[38:39], v[140:141], 0, v[34:35]
	s_waitcnt vmcnt(12)
	v_mov_b32_e32 v34, v192
	v_mov_b32_e32 v35, v193
	v_mov_b32_e32 v36, v194
	v_mov_b32_e32 v37, v195
	v_lshlrev_b32_e32 v40, 16, v34
	v_and_b32_e32 v41, 0xffff0000, v34
	v_lshlrev_b32_e32 v34, 16, v35
	v_and_b32_e32 v35, 0xffff0000, v35
	v_pk_add_f32 v[30:31], v[30:31], v[34:35]
	v_lshlrev_b32_e32 v34, 16, v36
	v_and_b32_e32 v35, 0xffff0000, v36
	v_pk_add_f32 v[34:35], v[24:25], v[34:35]
	v_lshlrev_b32_e32 v24, 16, v37
	v_and_b32_e32 v25, 0xffff0000, v37
	v_pk_add_f32 v[28:29], v[28:29], v[40:41]
	v_pk_add_f32 v[36:37], v[26:27], v[24:25]
	v_cvt_pk_bf16_f32 v24, v28, v29
	v_cvt_pk_bf16_f32 v25, v30, v31
	v_cvt_pk_bf16_f32 v26, v34, v35
	v_cvt_pk_bf16_f32 v27, v36, v37
	global_store_dwordx4 v[38:39], v[24:27], off
	s_nop 1
	v_pk_mul_f32 v[24:25], v[28:29], v[28:29]
	v_pk_mul_f32 v[26:27], v[30:31], v[30:31]
	v_pk_mul_f32 v[28:29], v[34:35], v[34:35]
	v_pk_mul_f32 v[30:31], v[36:37], v[36:37]
	s_waitcnt vmcnt(12)
	v_mov_b32_e32 v34, v196
	v_mov_b32_e32 v35, v197
	v_mov_b32_e32 v36, v198
	v_mov_b32_e32 v37, v199
	v_lshlrev_b32_e32 v40, 16, v34
	v_and_b32_e32 v41, 0xffff0000, v34
	v_lshlrev_b32_e32 v34, 16, v35
	v_and_b32_e32 v35, 0xffff0000, v35
	v_pk_add_f32 v[22:23], v[22:23], v[34:35]
	v_lshlrev_b32_e32 v34, 16, v36
	v_and_b32_e32 v35, 0xffff0000, v36
	v_pk_add_f32 v[34:35], v[16:17], v[34:35]
	v_lshlrev_b32_e32 v16, 16, v37
	v_and_b32_e32 v17, 0xffff0000, v37
	v_pk_add_f32 v[20:21], v[20:21], v[40:41]
	v_pk_add_f32 v[36:37], v[18:19], v[16:17]
	v_cvt_pk_bf16_f32 v16, v20, v21
	v_cvt_pk_bf16_f32 v17, v22, v23
	v_cvt_pk_bf16_f32 v18, v34, v35
	v_cvt_pk_bf16_f32 v19, v36, v37
	global_store_dwordx4 v[38:39], v[16:19], off offset:256
	s_nop 1
	v_pk_mul_f32 v[16:17], v[20:21], v[20:21]
	v_pk_mul_f32 v[18:19], v[22:23], v[22:23]
	v_add_f32_e32 v16, v16, v17
	v_add_f32_e32 v18, v18, v19
	v_pk_mul_f32 v[20:21], v[34:35], v[34:35]
	v_pk_mul_f32 v[22:23], v[36:37], v[36:37]
	v_add_f32_e32 v16, v16, v18
	v_add_f32_e32 v17, v30, v31
	v_add_f32_e32 v18, v28, v29
	v_add_f32_e32 v22, v22, v23
	v_add_f32_e32 v20, v20, v21
	v_add_f32_e32 v17, v18, v17
	v_add_f32_e32 v18, v26, v27
	v_add_f32_e32 v19, v24, v25
	v_add_f32_e32 v20, v20, v22
	v_add_f32_e32 v18, v19, v18
	v_add_f32_e32 v16, v16, v20
	v_add_f32_e32 v17, v18, v17
	v_add_f32_e32 v16, v17, v16
	ds_bpermute_b32 v17, v146, v16
	s_waitcnt lgkmcnt(0)
	v_add_f32_e32 v16, v16, v17
	ds_bpermute_b32 v17, v147, v16
	s_and_saveexec_b64 s[4:5], s[6:7]
	s_cbranch_execz .LBB0_1218
	s_waitcnt lgkmcnt(0)
	v_add_f32_e32 v16, v16, v17
	v_mul_f32_e32 v16, 0x4b800000, v16
	v_trunc_f32_e32 v16, v16
	v_mul_f32_e32 v17, 0x2f800000, v16
	v_floor_f32_e32 v17, v17
	v_fmac_f32_e32 v16, 0xcf800000, v17
	v_cvt_u32_f32_e32 v16, v16
	v_cvt_u32_f32_e32 v17, v17
	v_lshl_add_u64 v[18:19], v[32:33], 3, s[28:29]
	global_atomic_add_x2 v[18:19], v[16:17], off
.LBB0_1218:
	s_or_b64 exec, exec, s[4:5]
	v_add_u32_e32 v16, 0xb0, v142
	s_waitcnt lgkmcnt(0)
	v_ashrrev_i32_e32 v17, 31, v16
	v_lshlrev_b64 v[18:19], 11, v[16:17]
	v_lshl_add_u64 v[22:23], v[140:141], 0, v[18:19]
	s_waitcnt vmcnt(12)
	v_mov_b32_e32 v18, v200
	v_mov_b32_e32 v19, v201
	v_mov_b32_e32 v20, v202
	v_mov_b32_e32 v21, v203
	v_lshlrev_b32_e32 v24, 16, v18
	v_and_b32_e32 v25, 0xffff0000, v18
	v_lshlrev_b32_e32 v18, 16, v19
	v_and_b32_e32 v19, 0xffff0000, v19
	v_pk_add_f32 v[14:15], v[14:15], v[18:19]
	v_lshlrev_b32_e32 v18, 16, v20
	v_and_b32_e32 v19, 0xffff0000, v20
	v_pk_add_f32 v[18:19], v[8:9], v[18:19]
	v_lshlrev_b32_e32 v8, 16, v21
	v_and_b32_e32 v9, 0xffff0000, v21
	v_pk_add_f32 v[12:13], v[12:13], v[24:25]
	v_pk_add_f32 v[20:21], v[10:11], v[8:9]
	v_cvt_pk_bf16_f32 v8, v12, v13
	v_cvt_pk_bf16_f32 v9, v14, v15
	v_cvt_pk_bf16_f32 v10, v18, v19
	v_cvt_pk_bf16_f32 v11, v20, v21
	global_store_dwordx4 v[22:23], v[8:11], off
	s_nop 1
	v_pk_mul_f32 v[8:9], v[12:13], v[12:13]
	v_pk_mul_f32 v[10:11], v[14:15], v[14:15]
	v_pk_mul_f32 v[12:13], v[18:19], v[18:19]
	v_pk_mul_f32 v[14:15], v[20:21], v[20:21]
	s_waitcnt vmcnt(12)
	v_mov_b32_e32 v18, v216
	v_mov_b32_e32 v19, v217
	v_mov_b32_e32 v20, v218
	v_mov_b32_e32 v21, v219
	v_lshlrev_b32_e32 v24, 16, v18
	v_and_b32_e32 v25, 0xffff0000, v18
	v_lshlrev_b32_e32 v18, 16, v19
	v_and_b32_e32 v19, 0xffff0000, v19
	v_pk_add_f32 v[6:7], v[6:7], v[18:19]
	v_lshlrev_b32_e32 v18, 16, v20
	v_and_b32_e32 v19, 0xffff0000, v20
	v_pk_add_f32 v[18:19], v[0:1], v[18:19]
	v_lshlrev_b32_e32 v0, 16, v21
	v_and_b32_e32 v1, 0xffff0000, v21
	v_pk_add_f32 v[4:5], v[4:5], v[24:25]
	v_pk_add_f32 v[20:21], v[2:3], v[0:1]
	v_cvt_pk_bf16_f32 v0, v4, v5
	v_cvt_pk_bf16_f32 v1, v6, v7
	v_cvt_pk_bf16_f32 v2, v18, v19
	v_cvt_pk_bf16_f32 v3, v20, v21
	global_store_dwordx4 v[22:23], v[0:3], off offset:256
	s_nop 1
	v_pk_mul_f32 v[0:1], v[4:5], v[4:5]
	v_pk_mul_f32 v[2:3], v[6:7], v[6:7]
	v_add_f32_e32 v0, v0, v1
	v_add_f32_e32 v2, v2, v3
	v_pk_mul_f32 v[4:5], v[18:19], v[18:19]
	v_pk_mul_f32 v[6:7], v[20:21], v[20:21]
	v_add_f32_e32 v0, v0, v2
	v_add_f32_e32 v1, v14, v15
	v_add_f32_e32 v2, v12, v13
	v_add_f32_e32 v6, v6, v7
	v_add_f32_e32 v4, v4, v5
	v_add_f32_e32 v1, v2, v1
	v_add_f32_e32 v2, v10, v11
	v_add_f32_e32 v3, v8, v9
	v_add_f32_e32 v4, v4, v6
	v_add_f32_e32 v2, v3, v2
	v_add_f32_e32 v0, v0, v4
	v_add_f32_e32 v1, v2, v1
	v_add_f32_e32 v0, v1, v0
	ds_bpermute_b32 v1, v146, v0
	s_waitcnt lgkmcnt(0)
	v_add_f32_e32 v0, v0, v1
	ds_bpermute_b32 v1, v147, v0
	s_and_saveexec_b64 s[4:5], s[6:7]
	s_cbranch_execz .LBB0_1220
	s_waitcnt lgkmcnt(0)
	v_add_f32_e32 v0, v0, v1
	v_mul_f32_e32 v0, 0x4b800000, v0
	v_trunc_f32_e32 v0, v0
	v_mul_f32_e32 v1, 0x2f800000, v0
	v_floor_f32_e32 v1, v1
	v_fmac_f32_e32 v0, 0xcf800000, v1
	v_cvt_u32_f32_e32 v0, v0
	v_cvt_u32_f32_e32 v1, v1
	v_lshl_add_u64 v[2:3], v[16:17], 3, s[28:29]
	global_atomic_add_x2 v[2:3], v[0:1], off

;     __device__ __forceinline__ static u32x4 pack8(const f32x4& a, const f32x4& b) { u32x4 w; w.x = cvtpk(a[0], a[1]); w.y = cvtpk(a[2], a[3]); w.z = cvtpk(b[0], b[1]); w.w = cvtpk(b[2], b[3]); return w; }
;     __device__ __forceinline__ static float sumsq8(const f32x4& a, const f32x4& b) { return ((a[0] * a[0] + a[1] * a[1]) + (a[2] * a[2] + a[3] * a[3])) + ((b[0] * b[0] + b[1] * b[1]) + (b[2] * b[2] + b[3] * b[3])); }
;     __device__ __forceinline__ static void row_atomic(sq_t* sq, int row, float s, int lane, int fq) { s += shx(s, lane, 16); s += shx(s, lane, 32); if (fq == 0) (void)__hip_atomic_fetch_add(sq + row, (sq_t)(s * 16777216.f), __ATOMIC_RELAXED, __HIP_MEMORY_SCOPE_AGENT); }
;     __device__ __forceinline__ void operator()(const f32x4 (&acc)[2][2][4][2], const Unit& u, int wr, int wc, int fr, int fq) const {
;     ...
;         } else if (mode == EM_WO || mode == EM_FF2) {
;             const bf16_t* hb = (const bf16_t*)(ws + WS_H); bf16_t* dst = (mode == EM_FF2 && flag) ? (bf16_t*)(ws + WS_MRG) : (bf16_t*)(ws + WS_H);
;             sq_t* sq = mode == EM_WO ? SQMID : (flag ? SQX + 4 * TCH : SQX);
; #pragma unroll
;             for (int ai = 0; ai < 2; ++ai)
; #pragma unroll
;                 for (int m = 0; m < 4; ++m) { const int row = row0 + ai * HALF + m * 16; float ss = 0.f;
; #pragma unroll
;                     for (int bj = 0; bj < 2; ++bj) { const size_t o = (size_t)row * 1024 + pn * 256 + bj * HALF + cw;
;                         const u32x4 xi = *(const u32x4*)(hb + o); f32x4 r0 = acc[ai][bj][m][0], r1 = acc[ai][bj][m][1];
;                         r0[0] += bflo(xi.x); r0[1] += bfhi(xi.x); r0[2] += bflo(xi.y); r0[3] += bfhi(xi.y); r1[0] += bflo(xi.z); r1[1] += bfhi(xi.z); r1[2] += bflo(xi.w); r1[3] += bfhi(xi.w);
;                         *(u32x4*)(dst + o) = pack8(r0, r1); ss += sumsq8(r0, r1); }
;                     row_atomic(sq, row, ss, lane, fq); }
.LBB0_1449:
	v_lshl_add_u32 v146, s3, 8, v135
	s_lshl_b32 s2, s2, 8
	s_ashr_i32 s3, s2, 31
	v_ashrrev_i32_e32 v147, 31, v146
	v_mov_b32_e32 v145, s3
	v_or_b32_e32 v144, s2, v134
	v_lshlrev_b64 v[140:141], 10, v[146:147]
	v_lshl_add_u64 v[140:141], v[140:141], 0, v[144:145]
	v_lshlrev_b64 v[142:143], 1, v[140:141]
	v_lshl_add_u64 v[140:141], s[28:29], 0, v[142:143]
	v_mov_b32_e32 v208, v140
	v_mov_b32_e32 v209, v141
	global_load_dwordx4 v[192:195], v[208:209], off
	global_load_dwordx4 v[196:199], v[208:209], off offset:256
	s_mov_b32 s98, 0x8000
	s_mov_b32 s99, 0
	v_lshl_add_u64 v[204:205], v[208:209], 0, s[98:99]
	global_load_dwordx4 v[200:203], v[204:205], off
	global_load_dwordx4 v[216:219], v[204:205], off offset:256
	s_mov_b32 s98, 0x10000
	s_mov_b32 s99, 0
	v_lshl_add_u64 v[204:205], v[208:209], 0, s[98:99]
	global_load_dwordx4 v[220:223], v[204:205], off
	global_load_dwordx4 v[224:227], v[204:205], off offset:256
	s_mov_b32 s98, 0x18000
	s_mov_b32 s99, 0
	v_lshl_add_u64 v[204:205], v[208:209], 0, s[98:99]
	global_load_dwordx4 v[228:231], v[204:205], off
	global_load_dwordx4 v[234:237], v[204:205], off offset:256
	s_mov_b32 s98, 0x40000
	s_mov_b32 s99, 0
	v_lshl_add_u64 v[204:205], v[208:209], 0, s[98:99]
	global_load_dwordx4 v[238:241], v[204:205], off
	global_load_dwordx4 v[242:245], v[204:205], off offset:256
	s_mov_b32 s98, 0x48000
	s_mov_b32 s99, 0
	v_lshl_add_u64 v[204:205], v[208:209], 0, s[98:99]
	global_load_dwordx4 v[246:249], v[204:205], off
	global_load_dwordx4 v[250:253], v[204:205], off offset:256
	s_waitcnt vmcnt(11)
	v_mov_b32_e32 v154, v192
	v_mov_b32_e32 v155, v193
	v_mov_b32_e32 v156, v194
	v_mov_b32_e32 v157, v195
	s_mov_b32 s98, 0x50000
	s_mov_b32 s99, 0
	v_lshl_add_u64 v[204:205], v[208:209], 0, s[98:99]
	global_load_dwordx4 v[192:195], v[204:205], off
	v_lshlrev_b32_e32 v158, 16, v154
	v_and_b32_e32 v159, 0xffff0000, v154
	v_lshlrev_b32_e32 v154, 16, v155
	v_and_b32_e32 v155, 0xffff0000, v155
	v_pk_add_f32 v[126:127], v[126:127], v[154:155]
	v_lshlrev_b32_e32 v154, 16, v156
	v_and_b32_e32 v155, 0xffff0000, v156
	v_pk_add_f32 v[154:155], v[120:121], v[154:155]
	v_lshlrev_b32_e32 v120, 16, v157
	v_and_b32_e32 v121, 0xffff0000, v157
	v_pk_add_f32 v[124:125], v[124:125], v[158:159]
	v_pk_add_f32 v[156:157], v[122:123], v[120:121]
	v_cvt_pk_bf16_f32 v120, v124, v125
	v_cvt_pk_bf16_f32 v121, v126, v127
	v_cvt_pk_bf16_f32 v122, v154, v155
	v_cvt_pk_bf16_f32 v123, v156, v157
	v_lshl_add_u64 v[158:159], s[34:35], 0, v[142:143]
	global_store_dwordx4 v[158:159], v[120:123], off
	s_nop 1
	v_pk_mul_f32 v[120:121], v[124:125], v[124:125]
	v_pk_mul_f32 v[124:125], v[154:155], v[154:155]
	v_or_b32_e32 v154, 0x100, v142
	v_mov_b32_e32 v155, v143
	v_lshl_add_u64 v[154:155], s[28:29], 0, v[154:155]
	v_pk_mul_f32 v[122:123], v[126:127], v[126:127]
	v_pk_mul_f32 v[126:127], v[156:157], v[156:157]
	s_waitcnt vmcnt(12)
	v_mov_b32_e32 v154, v196
	v_mov_b32_e32 v155, v197
	v_mov_b32_e32 v156, v198
	v_mov_b32_e32 v157, v199
	global_load_dwordx4 v[196:199], v[204:205], off offset:256
	v_lshlrev_b32_e32 v160, 16, v154
	v_and_b32_e32 v161, 0xffff0000, v154
	v_lshlrev_b32_e32 v154, 16, v155
	v_and_b32_e32 v155, 0xffff0000, v155
	v_pk_add_f32 v[118:119], v[118:119], v[154:155]
	v_lshlrev_b32_e32 v154, 16, v156
	v_and_b32_e32 v155, 0xffff0000, v156
	v_pk_add_f32 v[154:155], v[112:113], v[154:155]
	v_lshlrev_b32_e32 v112, 16, v157
	v_and_b32_e32 v113, 0xffff0000, v157
	v_pk_add_f32 v[116:117], v[116:117], v[160:161]
	v_pk_add_f32 v[156:157], v[114:115], v[112:113]
	v_cvt_pk_bf16_f32 v112, v116, v117
	v_cvt_pk_bf16_f32 v113, v118, v119
	v_cvt_pk_bf16_f32 v114, v154, v155
	v_cvt_pk_bf16_f32 v115, v156, v157
	global_store_dwordx4 v[158:159], v[112:115], off offset:256
	s_nop 1
	v_pk_mul_f32 v[112:113], v[116:117], v[116:117]
	v_pk_mul_f32 v[114:115], v[118:119], v[118:119]
	v_add_f32_e32 v112, v112, v113
	v_add_f32_e32 v114, v114, v115
	v_pk_mul_f32 v[116:117], v[154:155], v[154:155]
	v_pk_mul_f32 v[118:119], v[156:157], v[156:157]
	v_add_f32_e32 v112, v112, v114
	v_add_f32_e32 v113, v126, v127
	v_add_f32_e32 v114, v124, v125
	v_add_f32_e32 v118, v118, v119
	v_add_f32_e32 v116, v116, v117
	v_add_f32_e32 v113, v114, v113
	v_add_f32_e32 v114, v122, v123
	v_add_f32_e32 v115, v120, v121
	v_add_f32_e32 v116, v116, v118
	v_add_f32_e32 v114, v115, v114
	v_add_f32_e32 v112, v112, v116
	v_add_f32_e32 v113, v114, v113
	v_add_f32_e32 v112, v113, v112
	ds_bpermute_b32 v113, v151, v112
	s_waitcnt lgkmcnt(0)
	v_add_f32_e32 v114, v112, v113
	ds_bpermute_b32 v115, v152, v114
	v_lshl_add_u64 v[112:113], v[146:147], 3, s[30:31]
	s_and_saveexec_b64 s[4:5], s[6:7]
	s_cbranch_execz .LBB0_1451
	s_waitcnt lgkmcnt(0)
	v_add_f32_e32 v114, v114, v115
	v_mul_f32_e32 v114, 0x4b800000, v114
	v_trunc_f32_e32 v114, v114
	v_mul_f32_e32 v115, 0x2f800000, v114
	v_floor_f32_e32 v115, v115
	v_fmac_f32_e32 v114, 0xcf800000, v115
	v_cvt_u32_f32_e32 v114, v114
	v_cvt_u32_f32_e32 v115, v115
	global_atomic_add_x2 v[112:113], v[114:115], off
;     __device__ __forceinline__ static u32x4 pack8(const f32x4& a, const f32x4& b) { u32x4 w; w.x = cvtpk(a[0], a[1]); w.y = cvtpk(a[2], a[3]); w.z = cvtpk(b[0], b[1]); w.w = cvtpk(b[2], b[3]); return w; }
;     __device__ __forceinline__ static float sumsq8(const f32x4& a, const f32x4& b) { return ((a[0] * a[0] + a[1] * a[1]) + (a[2] * a[2] + a[3] * a[3])) + ((b[0] * b[0] + b[1] * b[1]) + (b[2] * b[2] + b[3] * b[3])); }
;     __device__ __forceinline__ static void row_atomic(sq_t* sq, int row, float s, int lane, int fq) { s += shx(s, lane, 16); s += shx(s, lane, 32); if (fq == 0) (void)__hip_atomic_fetch_add(sq + row, (sq_t)(s * 16777216.f), __ATOMIC_RELAXED, __HIP_MEMORY_SCOPE_AGENT); }
;     __device__ __forceinline__ void operator()(const f32x4 (&acc)[2][2][4][2], const Unit& u, int wr, int wc, int fr, int fq) const {
;     ...
;         } else if (mode == EM_WO || mode == EM_FF2) {
;             const bf16_t* hb = (const bf16_t*)(ws + WS_H); bf16_t* dst = (mode == EM_FF2 && flag) ? (bf16_t*)(ws + WS_MRG) : (bf16_t*)(ws + WS_H);
;             sq_t* sq = mode == EM_WO ? SQMID : (flag ? SQX + 4 * TCH : SQX);
; #pragma unroll
;             for (int ai = 0; ai < 2; ++ai)
; #pragma unroll
;                 for (int m = 0; m < 4; ++m) { const int row = row0 + ai * HALF + m * 16; float ss = 0.f;
; #pragma unroll
;                     for (int bj = 0; bj < 2; ++bj) { const size_t o = (size_t)row * 1024 + pn * 256 + bj * HALF + cw;
;                         const u32x4 xi = *(const u32x4*)(hb + o); f32x4 r0 = acc[ai][bj][m][0], r1 = acc[ai][bj][m][1];
;                         r0[0] += bflo(xi.x); r0[1] += bfhi(xi.x); r0[2] += bflo(xi.y); r0[3] += bfhi(xi.y); r1[0] += bflo(xi.z); r1[1] += bfhi(xi.z); r1[2] += bflo(xi.w); r1[3] += bfhi(xi.w);
;                         *(u32x4*)(dst + o) = pack8(r0, r1); ss += sumsq8(r0, r1); }
;                     row_atomic(sq, row, ss, lane, fq); }
.LBB0_1451:
	s_or_b64 exec, exec, s[4:5]
	v_or_b32_e32 v114, 16, v146
	s_waitcnt lgkmcnt(0)
	v_ashrrev_i32_e32 v115, 31, v114
	v_lshlrev_b64 v[114:115], 10, v[114:115]
	v_lshl_add_u64 v[114:115], v[114:115], 0, v[144:145]
	v_lshlrev_b64 v[118:119], 1, v[114:115]
	v_lshl_add_u64 v[114:115], s[28:29], 0, v[118:119]
	s_waitcnt vmcnt(13)
	v_mov_b32_e32 v114, v200
	v_mov_b32_e32 v115, v201
	v_mov_b32_e32 v116, v202
	v_mov_b32_e32 v117, v203
	s_mov_b32 s98, 0x58000
	s_mov_b32 s99, 0
	v_lshl_add_u64 v[204:205], v[208:209], 0, s[98:99]
	global_load_dwordx4 v[200:203], v[204:205], off
	v_lshlrev_b32_e32 v120, 16, v114
	v_and_b32_e32 v121, 0xffff0000, v114
	v_lshlrev_b32_e32 v114, 16, v115
	v_and_b32_e32 v115, 0xffff0000, v115
	v_pk_add_f32 v[110:111], v[110:111], v[114:115]
	v_lshlrev_b32_e32 v114, 16, v116
	v_and_b32_e32 v115, 0xffff0000, v116
	v_pk_add_f32 v[114:115], v[104:105], v[114:115]
	v_lshlrev_b32_e32 v104, 16, v117
	v_and_b32_e32 v105, 0xffff0000, v117
	v_pk_add_f32 v[108:109], v[108:109], v[120:121]
	v_pk_add_f32 v[116:117], v[106:107], v[104:105]
	v_cvt_pk_bf16_f32 v104, v108, v109
	v_cvt_pk_bf16_f32 v105, v110, v111
	v_cvt_pk_bf16_f32 v106, v114, v115
	v_cvt_pk_bf16_f32 v107, v116, v117
	v_lshl_add_u64 v[120:121], s[34:35], 0, v[118:119]
	v_or_b32_e32 v118, 0x100, v118
	global_store_dwordx4 v[120:121], v[104:107], off
	s_nop 1
	v_pk_mul_f32 v[104:105], v[108:109], v[108:109]
	v_pk_mul_f32 v[108:109], v[114:115], v[114:115]
	v_lshl_add_u64 v[114:115], s[28:29], 0, v[118:119]
	v_pk_mul_f32 v[106:107], v[110:111], v[110:111]
	v_pk_mul_f32 v[110:111], v[116:117], v[116:117]
	s_waitcnt vmcnt(14)
	v_mov_b32_e32 v114, v216
	v_mov_b32_e32 v115, v217
	v_mov_b32_e32 v116, v218
	v_mov_b32_e32 v117, v219
	global_load_dwordx4 v[216:219], v[204:205], off offset:256
	v_lshlrev_b32_e32 v118, 16, v114
	v_and_b32_e32 v119, 0xffff0000, v114
	v_lshlrev_b32_e32 v114, 16, v115
	v_and_b32_e32 v115, 0xffff0000, v115
	v_pk_add_f32 v[102:103], v[102:103], v[114:115]
	v_lshlrev_b32_e32 v114, 16, v116
	v_and_b32_e32 v115, 0xffff0000, v116
	v_pk_add_f32 v[114:115], v[96:97], v[114:115]
	v_lshlrev_b32_e32 v96, 16, v117
	v_and_b32_e32 v97, 0xffff0000, v117
	v_pk_add_f32 v[100:101], v[100:101], v[118:119]
	v_pk_add_f32 v[116:117], v[98:99], v[96:97]
	v_cvt_pk_bf16_f32 v96, v100, v101
	v_cvt_pk_bf16_f32 v97, v102, v103
	v_cvt_pk_bf16_f32 v98, v114, v115
	v_cvt_pk_bf16_f32 v99, v116, v117
	global_store_dwordx4 v[120:121], v[96:99], off offset:256
	s_nop 1
	v_pk_mul_f32 v[96:97], v[100:101], v[100:101]
	v_pk_mul_f32 v[98:99], v[102:103], v[102:103]
	v_add_f32_e32 v96, v96, v97
	v_add_f32_e32 v98, v98, v99
	v_pk_mul_f32 v[100:101], v[114:115], v[114:115]
	v_pk_mul_f32 v[102:103], v[116:117], v[116:117]
	v_add_f32_e32 v96, v96, v98
	v_add_f32_e32 v97, v110, v111
	v_add_f32_e32 v98, v108, v109
	v_add_f32_e32 v102, v102, v103
	v_add_f32_e32 v100, v100, v101
	v_add_f32_e32 v97, v98, v97
	v_add_f32_e32 v98, v106, v107
	v_add_f32_e32 v99, v104, v105
	v_add_f32_e32 v100, v100, v102
	v_add_f32_e32 v98, v99, v98
	v_add_f32_e32 v96, v96, v100
	v_add_f32_e32 v97, v98, v97
	v_add_f32_e32 v96, v97, v96
	ds_bpermute_b32 v97, v151, v96
	s_waitcnt lgkmcnt(0)
	v_add_f32_e32 v96, v96, v97
	ds_bpermute_b32 v97, v152, v96
	s_and_saveexec_b64 s[4:5], s[6:7]
	s_cbranch_execz .LBB0_1453
	s_waitcnt lgkmcnt(0)
	v_add_f32_e32 v96, v96, v97
	v_mul_f32_e32 v96, 0x4b800000, v96
	v_trunc_f32_e32 v96, v96
	v_mul_f32_e32 v97, 0x2f800000, v96
	v_floor_f32_e32 v97, v97
	v_fmac_f32_e32 v96, 0xcf800000, v97
	v_cvt_u32_f32_e32 v96, v96
	v_cvt_u32_f32_e32 v97, v97
	global_atomic_add_x2 v[112:113], v[96:97], off offset:128
.LBB0_1453:
	s_or_b64 exec, exec, s[4:5]
	v_or_b32_e32 v96, 32, v146
	s_waitcnt lgkmcnt(0)
	v_ashrrev_i32_e32 v97, 31, v96
	v_lshlrev_b64 v[96:97], 10, v[96:97]
	v_lshl_add_u64 v[96:97], v[96:97], 0, v[144:145]
	v_lshlrev_b64 v[100:101], 1, v[96:97]
	v_lshl_add_u64 v[96:97], s[28:29], 0, v[100:101]
	s_waitcnt vmcnt(15)
	v_mov_b32_e32 v96, v220
	v_mov_b32_e32 v97, v221
	v_mov_b32_e32 v98, v222
	v_mov_b32_e32 v99, v223
	v_lshlrev_b32_e32 v102, 16, v96
	v_and_b32_e32 v103, 0xffff0000, v96
	v_lshlrev_b32_e32 v96, 16, v97
	v_and_b32_e32 v97, 0xffff0000, v97
	v_pk_add_f32 v[94:95], v[94:95], v[96:97]
	v_lshlrev_b32_e32 v96, 16, v98
	v_and_b32_e32 v97, 0xffff0000, v98
	v_pk_add_f32 v[96:97], v[88:89], v[96:97]
	v_lshlrev_b32_e32 v88, 16, v99
	v_and_b32_e32 v89, 0xffff0000, v99
	v_pk_add_f32 v[92:93], v[92:93], v[102:103]
	v_pk_add_f32 v[98:99], v[90:91], v[88:89]
	v_cvt_pk_bf16_f32 v88, v92, v93
	v_cvt_pk_bf16_f32 v89, v94, v95
	v_cvt_pk_bf16_f32 v90, v96, v97
	v_cvt_pk_bf16_f32 v91, v98, v99
	v_lshl_add_u64 v[102:103], s[34:35], 0, v[100:101]
	v_or_b32_e32 v100, 0x100, v100
	global_store_dwordx4 v[102:103], v[88:91], off
	s_nop 1
	v_pk_mul_f32 v[88:89], v[92:93], v[92:93]
	v_pk_mul_f32 v[92:93], v[96:97], v[96:97]
	v_lshl_add_u64 v[96:97], s[28:29], 0, v[100:101]
	v_pk_mul_f32 v[90:91], v[94:95], v[94:95]
	v_pk_mul_f32 v[94:95], v[98:99], v[98:99]
	s_waitcnt vmcnt(15)
	v_mov_b32_e32 v96, v224
	v_mov_b32_e32 v97, v225
	v_mov_b32_e32 v98, v226
	v_mov_b32_e32 v99, v227
	v_lshlrev_b32_e32 v100, 16, v96
	v_and_b32_e32 v101, 0xffff0000, v96
	v_lshlrev_b32_e32 v96, 16, v97
	v_and_b32_e32 v97, 0xffff0000, v97
	v_pk_add_f32 v[86:87], v[86:87], v[96:97]
	v_lshlrev_b32_e32 v96, 16, v98
	v_and_b32_e32 v97, 0xffff0000, v98
	v_pk_add_f32 v[96:97], v[80:81], v[96:97]
	v_lshlrev_b32_e32 v80, 16, v99
	v_and_b32_e32 v81, 0xffff0000, v99
	v_pk_add_f32 v[84:85], v[84:85], v[100:101]
	v_pk_add_f32 v[98:99], v[82:83], v[80:81]
	v_cvt_pk_bf16_f32 v80, v84, v85
	v_cvt_pk_bf16_f32 v81, v86, v87
	v_cvt_pk_bf16_f32 v82, v96, v97
	v_cvt_pk_bf16_f32 v83, v98, v99
	global_store_dwordx4 v[102:103], v[80:83], off offset:256
	s_nop 1
	v_pk_mul_f32 v[80:81], v[84:85], v[84:85]
	v_pk_mul_f32 v[82:83], v[86:87], v[86:87]
	v_add_f32_e32 v80, v80, v81
	v_add_f32_e32 v82, v82, v83
	v_pk_mul_f32 v[84:85], v[96:97], v[96:97]
	v_pk_mul_f32 v[86:87], v[98:99], v[98:99]
	v_add_f32_e32 v80, v80, v82
	v_add_f32_e32 v81, v94, v95
	v_add_f32_e32 v82, v92, v93
	v_add_f32_e32 v86, v86, v87
	v_add_f32_e32 v84, v84, v85
	v_add_f32_e32 v81, v82, v81
	v_add_f32_e32 v82, v90, v91
	v_add_f32_e32 v83, v88, v89
	v_add_f32_e32 v84, v84, v86
	v_add_f32_e32 v82, v83, v82
	v_add_f32_e32 v80, v80, v84
	v_add_f32_e32 v81, v82, v81
	v_add_f32_e32 v80, v81, v80
	ds_bpermute_b32 v81, v151, v80
	s_waitcnt lgkmcnt(0)
	v_add_f32_e32 v80, v80, v81
	ds_bpermute_b32 v81, v152, v80
	s_and_saveexec_b64 s[4:5], s[6:7]
	s_cbranch_execz .LBB0_1455
	s_waitcnt lgkmcnt(0)
	v_add_f32_e32 v80, v80, v81
	v_mul_f32_e32 v80, 0x4b800000, v80
	v_trunc_f32_e32 v80, v80
	v_mul_f32_e32 v81, 0x2f800000, v80
	v_floor_f32_e32 v81, v81
	v_fmac_f32_e32 v80, 0xcf800000, v81
	v_cvt_u32_f32_e32 v80, v80
	v_cvt_u32_f32_e32 v81, v81
	global_atomic_add_x2 v[112:113], v[80:81], off offset:256
;     __device__ __forceinline__ static u32x4 pack8(const f32x4& a, const f32x4& b) { u32x4 w; w.x = cvtpk(a[0], a[1]); w.y = cvtpk(a[2], a[3]); w.z = cvtpk(b[0], b[1]); w.w = cvtpk(b[2], b[3]); return w; }
;     __device__ __forceinline__ static float sumsq8(const f32x4& a, const f32x4& b) { return ((a[0] * a[0] + a[1] * a[1]) + (a[2] * a[2] + a[3] * a[3])) + ((b[0] * b[0] + b[1] * b[1]) + (b[2] * b[2] + b[3] * b[3])); }
;     __device__ __forceinline__ static void row_atomic(sq_t* sq, int row, float s, int lane, int fq) { s += shx(s, lane, 16); s += shx(s, lane, 32); if (fq == 0) (void)__hip_atomic_fetch_add(sq + row, (sq_t)(s * 16777216.f), __ATOMIC_RELAXED, __HIP_MEMORY_SCOPE_AGENT); }
;     __device__ __forceinline__ void operator()(const f32x4 (&acc)[2][2][4][2], const Unit& u, int wr, int wc, int fr, int fq) const {
;     ...
;         } else if (mode == EM_WO || mode == EM_FF2) {
;             const bf16_t* hb = (const bf16_t*)(ws + WS_H); bf16_t* dst = (mode == EM_FF2 && flag) ? (bf16_t*)(ws + WS_MRG) : (bf16_t*)(ws + WS_H);
;             sq_t* sq = mode == EM_WO ? SQMID : (flag ? SQX + 4 * TCH : SQX);
; #pragma unroll
;             for (int ai = 0; ai < 2; ++ai)
; #pragma unroll
;                 for (int m = 0; m < 4; ++m) { const int row = row0 + ai * HALF + m * 16; float ss = 0.f;
; #pragma unroll
;                     for (int bj = 0; bj < 2; ++bj) { const size_t o = (size_t)row * 1024 + pn * 256 + bj * HALF + cw;
;                         const u32x4 xi = *(const u32x4*)(hb + o); f32x4 r0 = acc[ai][bj][m][0], r1 = acc[ai][bj][m][1];
;                         r0[0] += bflo(xi.x); r0[1] += bfhi(xi.x); r0[2] += bflo(xi.y); r0[3] += bfhi(xi.y); r1[0] += bflo(xi.z); r1[1] += bfhi(xi.z); r1[2] += bflo(xi.w); r1[3] += bfhi(xi.w);
;                         *(u32x4*)(dst + o) = pack8(r0, r1); ss += sumsq8(r0, r1); }
;                     row_atomic(sq, row, ss, lane, fq); }
.LBB0_1455:
	s_or_b64 exec, exec, s[4:5]
	v_or_b32_e32 v80, 48, v146
	s_waitcnt lgkmcnt(0)
	v_ashrrev_i32_e32 v81, 31, v80
	v_lshlrev_b64 v[80:81], 10, v[80:81]
	v_lshl_add_u64 v[80:81], v[80:81], 0, v[144:145]
	v_lshlrev_b64 v[84:85], 1, v[80:81]
	v_lshl_add_u64 v[80:81], s[28:29], 0, v[84:85]
	s_waitcnt vmcnt(15)
	v_mov_b32_e32 v80, v228
	v_mov_b32_e32 v81, v229
	v_mov_b32_e32 v82, v230
	v_mov_b32_e32 v83, v231
	v_lshlrev_b32_e32 v86, 16, v80
	v_and_b32_e32 v87, 0xffff0000, v80
	v_lshlrev_b32_e32 v80, 16, v81
	v_and_b32_e32 v81, 0xffff0000, v81
	v_pk_add_f32 v[78:79], v[78:79], v[80:81]
	v_lshlrev_b32_e32 v80, 16, v82
	v_and_b32_e32 v81, 0xffff0000, v82
	v_pk_add_f32 v[80:81], v[72:73], v[80:81]
	v_lshlrev_b32_e32 v72, 16, v83
	v_and_b32_e32 v73, 0xffff0000, v83
	v_pk_add_f32 v[76:77], v[76:77], v[86:87]
	v_pk_add_f32 v[82:83], v[74:75], v[72:73]
	v_cvt_pk_bf16_f32 v72, v76, v77
	v_cvt_pk_bf16_f32 v73, v78, v79
	v_cvt_pk_bf16_f32 v74, v80, v81
	v_cvt_pk_bf16_f32 v75, v82, v83
	v_lshl_add_u64 v[86:87], s[34:35], 0, v[84:85]
	v_or_b32_e32 v84, 0x100, v84
	global_store_dwordx4 v[86:87], v[72:75], off
	s_nop 1
	v_pk_mul_f32 v[72:73], v[76:77], v[76:77]
	v_pk_mul_f32 v[76:77], v[80:81], v[80:81]
	v_lshl_add_u64 v[80:81], s[28:29], 0, v[84:85]
	v_pk_mul_f32 v[74:75], v[78:79], v[78:79]
	v_pk_mul_f32 v[78:79], v[82:83], v[82:83]
	s_waitcnt vmcnt(15)
	v_mov_b32_e32 v80, v234
	v_mov_b32_e32 v81, v235
	v_mov_b32_e32 v82, v236
	v_mov_b32_e32 v83, v237
	v_lshlrev_b32_e32 v84, 16, v80
	v_and_b32_e32 v85, 0xffff0000, v80
	v_lshlrev_b32_e32 v80, 16, v81
	v_and_b32_e32 v81, 0xffff0000, v81
	v_pk_add_f32 v[70:71], v[70:71], v[80:81]
	v_lshlrev_b32_e32 v80, 16, v82
	v_and_b32_e32 v81, 0xffff0000, v82
	v_pk_add_f32 v[80:81], v[64:65], v[80:81]
	v_lshlrev_b32_e32 v64, 16, v83
	v_and_b32_e32 v65, 0xffff0000, v83
	v_pk_add_f32 v[68:69], v[68:69], v[84:85]
	v_pk_add_f32 v[82:83], v[66:67], v[64:65]
	v_cvt_pk_bf16_f32 v64, v68, v69
	v_cvt_pk_bf16_f32 v65, v70, v71
	v_cvt_pk_bf16_f32 v66, v80, v81
	v_cvt_pk_bf16_f32 v67, v82, v83
	global_store_dwordx4 v[86:87], v[64:67], off offset:256
	s_nop 1
	v_pk_mul_f32 v[64:65], v[68:69], v[68:69]
	v_pk_mul_f32 v[66:67], v[70:71], v[70:71]
	v_add_f32_e32 v64, v64, v65
	v_add_f32_e32 v66, v66, v67
	v_pk_mul_f32 v[68:69], v[80:81], v[80:81]
	v_pk_mul_f32 v[70:71], v[82:83], v[82:83]
	v_add_f32_e32 v64, v64, v66
	v_add_f32_e32 v65, v78, v79
	v_add_f32_e32 v66, v76, v77
	v_add_f32_e32 v70, v70, v71
	v_add_f32_e32 v68, v68, v69
	v_add_f32_e32 v65, v66, v65
	v_add_f32_e32 v66, v74, v75
	v_add_f32_e32 v67, v72, v73
	v_add_f32_e32 v68, v68, v70
	v_add_f32_e32 v66, v67, v66
	v_add_f32_e32 v64, v64, v68
	v_add_f32_e32 v65, v66, v65
	v_add_f32_e32 v64, v65, v64
	ds_bpermute_b32 v65, v151, v64
	s_waitcnt lgkmcnt(0)
	v_add_f32_e32 v64, v64, v65
	ds_bpermute_b32 v65, v152, v64
	s_and_saveexec_b64 s[4:5], s[6:7]
	s_cbranch_execz .LBB0_1457
	s_waitcnt lgkmcnt(0)
	v_add_f32_e32 v64, v64, v65
	v_mul_f32_e32 v64, 0x4b800000, v64
	v_trunc_f32_e32 v64, v64
	v_mul_f32_e32 v65, 0x2f800000, v64
	v_floor_f32_e32 v65, v65
	v_fmac_f32_e32 v64, 0xcf800000, v65
	v_cvt_u32_f32_e32 v64, v64
	v_cvt_u32_f32_e32 v65, v65
	global_atomic_add_x2 v[112:113], v[64:65], off offset:384
.LBB0_1457:
	s_or_b64 exec, exec, s[4:5]
	s_mov_b64 s[2:3], 0x40000
	v_lshl_add_u64 v[68:69], v[142:143], 0, s[2:3]
	s_waitcnt lgkmcnt(0)
	v_lshl_add_u64 v[64:65], s[28:29], 0, v[68:69]
	v_lshl_add_u64 v[68:69], s[34:35], 0, v[68:69]
	s_mov_b32 s2, 0x40000
	s_waitcnt vmcnt(15)
	v_mov_b32_e32 v64, v238
	v_mov_b32_e32 v65, v239
	v_mov_b32_e32 v66, v240
	v_mov_b32_e32 v67, v241
	v_lshlrev_b32_e32 v70, 16, v64
	v_and_b32_e32 v71, 0xffff0000, v64
	v_lshlrev_b32_e32 v64, 16, v65
	v_and_b32_e32 v65, 0xffff0000, v65
	v_pk_add_f32 v[62:63], v[62:63], v[64:65]
	v_lshlrev_b32_e32 v64, 16, v66
	v_and_b32_e32 v65, 0xffff0000, v66
	v_pk_add_f32 v[64:65], v[56:57], v[64:65]
	v_lshlrev_b32_e32 v56, 16, v67
	v_and_b32_e32 v57, 0xffff0000, v67
	v_pk_add_f32 v[60:61], v[60:61], v[70:71]
	v_pk_add_f32 v[66:67], v[58:59], v[56:57]
	v_cvt_pk_bf16_f32 v56, v60, v61
	v_cvt_pk_bf16_f32 v57, v62, v63
	v_cvt_pk_bf16_f32 v58, v64, v65
	v_cvt_pk_bf16_f32 v59, v66, v67
	global_store_dwordx4 v[68:69], v[56:59], off
	s_nop 1
	v_pk_mul_f32 v[56:57], v[60:61], v[60:61]
	v_pk_mul_f32 v[60:61], v[64:65], v[64:65]
	v_add_co_u32_e32 v64, vcc, s2, v140
	v_pk_mul_f32 v[58:59], v[62:63], v[62:63]
	s_nop 0
	v_addc_co_u32_e32 v65, vcc, 0, v141, vcc
	v_pk_mul_f32 v[62:63], v[66:67], v[66:67]
	v_add_f32_e32 v62, v62, v63
	v_add_f32_e32 v60, v60, v61
	v_add_f32_e32 v58, v58, v59
	v_add_f32_e32 v56, v56, v57
	v_add_f32_e32 v60, v60, v62
	v_add_f32_e32 v56, v56, v58
	v_add_f32_e32 v56, v56, v60
	s_waitcnt vmcnt(15)
	v_mov_b32_e32 v64, v242
	v_mov_b32_e32 v65, v243
	v_mov_b32_e32 v66, v244
	v_mov_b32_e32 v67, v245
	v_lshlrev_b32_e32 v70, 16, v64
	v_and_b32_e32 v71, 0xffff0000, v64
	v_lshlrev_b32_e32 v64, 16, v65
	v_and_b32_e32 v65, 0xffff0000, v65
	v_pk_add_f32 v[54:55], v[54:55], v[64:65]
	v_lshlrev_b32_e32 v64, 16, v66
	v_and_b32_e32 v65, 0xffff0000, v66
	v_pk_add_f32 v[64:65], v[48:49], v[64:65]
	v_lshlrev_b32_e32 v48, 16, v67
	v_and_b32_e32 v49, 0xffff0000, v67
	v_pk_add_f32 v[52:53], v[52:53], v[70:71]
	v_pk_add_f32 v[66:67], v[50:51], v[48:49]
	v_cvt_pk_bf16_f32 v48, v52, v53
	v_cvt_pk_bf16_f32 v49, v54, v55
	v_cvt_pk_bf16_f32 v50, v64, v65
	v_cvt_pk_bf16_f32 v51, v66, v67
	global_store_dwordx4 v[68:69], v[48:51], off offset:256
	s_nop 1
	v_pk_mul_f32 v[48:49], v[52:53], v[52:53]
	v_pk_mul_f32 v[50:51], v[54:55], v[54:55]
	v_pk_mul_f32 v[52:53], v[64:65], v[64:65]
	v_pk_mul_f32 v[54:55], v[66:67], v[66:67]
	v_add_f32_e32 v52, v52, v53
	v_add_f32_e32 v54, v54, v55
	v_add_f32_e32 v50, v50, v51
	v_add_f32_e32 v48, v48, v49
	v_add_f32_e32 v52, v52, v54
	v_add_f32_e32 v48, v48, v50
	v_add_f32_e32 v48, v48, v52
	v_add_f32_e32 v48, v56, v48
	ds_bpermute_b32 v49, v151, v48
	s_waitcnt lgkmcnt(0)
	v_add_f32_e32 v48, v48, v49
	ds_bpermute_b32 v49, v152, v48
	s_and_saveexec_b64 s[4:5], s[6:7]
	s_cbranch_execz .LBB0_1459
	s_waitcnt lgkmcnt(0)
	v_add_f32_e32 v48, v48, v49
	v_mul_f32_e32 v48, 0x4b800000, v48
	v_trunc_f32_e32 v48, v48
	v_mul_f32_e32 v49, 0x2f800000, v48
	v_floor_f32_e32 v49, v49
	v_fmac_f32_e32 v48, 0xcf800000, v49
	v_cvt_u32_f32_e32 v48, v48
	v_cvt_u32_f32_e32 v49, v49
	global_atomic_add_x2 v[112:113], v[48:49], off offset:1024
;     __device__ __forceinline__ static u32x4 pack8(const f32x4& a, const f32x4& b) { u32x4 w; w.x = cvtpk(a[0], a[1]); w.y = cvtpk(a[2], a[3]); w.z = cvtpk(b[0], b[1]); w.w = cvtpk(b[2], b[3]); return w; }
;     __device__ __forceinline__ static float sumsq8(const f32x4& a, const f32x4& b) { return ((a[0] * a[0] + a[1] * a[1]) + (a[2] * a[2] + a[3] * a[3])) + ((b[0] * b[0] + b[1] * b[1]) + (b[2] * b[2] + b[3] * b[3])); }
;     __device__ __forceinline__ static void row_atomic(sq_t* sq, int row, float s, int lane, int fq) { s += shx(s, lane, 16); s += shx(s, lane, 32); if (fq == 0) (void)__hip_atomic_fetch_add(sq + row, (sq_t)(s * 16777216.f), __ATOMIC_RELAXED, __HIP_MEMORY_SCOPE_AGENT); }
;     __device__ __forceinline__ void operator()(const f32x4 (&acc)[2][2][4][2], const Unit& u, int wr, int wc, int fr, int fq) const {
;     ...
;         } else if (mode == EM_WO || mode == EM_FF2) {
;             const bf16_t* hb = (const bf16_t*)(ws + WS_H); bf16_t* dst = (mode == EM_FF2 && flag) ? (bf16_t*)(ws + WS_MRG) : (bf16_t*)(ws + WS_H);
;             sq_t* sq = mode == EM_WO ? SQMID : (flag ? SQX + 4 * TCH : SQX);
; #pragma unroll
;             for (int ai = 0; ai < 2; ++ai)
; #pragma unroll
;                 for (int m = 0; m < 4; ++m) { const int row = row0 + ai * HALF + m * 16; float ss = 0.f;
; #pragma unroll
;                     for (int bj = 0; bj < 2; ++bj) { const size_t o = (size_t)row * 1024 + pn * 256 + bj * HALF + cw;
;                         const u32x4 xi = *(const u32x4*)(hb + o); f32x4 r0 = acc[ai][bj][m][0], r1 = acc[ai][bj][m][1];
;                         r0[0] += bflo(xi.x); r0[1] += bfhi(xi.x); r0[2] += bflo(xi.y); r0[3] += bfhi(xi.y); r1[0] += bflo(xi.z); r1[1] += bfhi(xi.z); r1[2] += bflo(xi.w); r1[3] += bfhi(xi.w);
;                         *(u32x4*)(dst + o) = pack8(r0, r1); ss += sumsq8(r0, r1); }
;                     row_atomic(sq, row, ss, lane, fq); }
.LBB0_1459:
	s_or_b64 exec, exec, s[4:5]
	s_mov_b64 s[2:3], 0x48000
	v_lshl_add_u64 v[52:53], v[142:143], 0, s[2:3]
	s_waitcnt lgkmcnt(0)
	v_lshl_add_u64 v[48:49], s[28:29], 0, v[52:53]
	v_lshl_add_u64 v[52:53], s[34:35], 0, v[52:53]
	s_mov_b32 s2, 0x48000
	s_waitcnt vmcnt(15)
	v_mov_b32_e32 v48, v246
	v_mov_b32_e32 v49, v247
	v_mov_b32_e32 v50, v248
	v_mov_b32_e32 v51, v249
	v_lshlrev_b32_e32 v54, 16, v48
	v_and_b32_e32 v55, 0xffff0000, v48
	v_lshlrev_b32_e32 v48, 16, v49
	v_and_b32_e32 v49, 0xffff0000, v49
	v_pk_add_f32 v[46:47], v[46:47], v[48:49]
	v_lshlrev_b32_e32 v48, 16, v50
	v_and_b32_e32 v49, 0xffff0000, v50
	v_pk_add_f32 v[48:49], v[40:41], v[48:49]
	v_lshlrev_b32_e32 v40, 16, v51
	v_and_b32_e32 v41, 0xffff0000, v51
	v_pk_add_f32 v[44:45], v[44:45], v[54:55]
	v_pk_add_f32 v[50:51], v[42:43], v[40:41]
	v_cvt_pk_bf16_f32 v40, v44, v45
	v_cvt_pk_bf16_f32 v41, v46, v47
	v_cvt_pk_bf16_f32 v42, v48, v49
	v_cvt_pk_bf16_f32 v43, v50, v51
	global_store_dwordx4 v[52:53], v[40:43], off
	s_nop 1
	v_pk_mul_f32 v[40:41], v[44:45], v[44:45]
	v_pk_mul_f32 v[44:45], v[48:49], v[48:49]
	v_add_co_u32_e32 v48, vcc, s2, v140
	v_pk_mul_f32 v[42:43], v[46:47], v[46:47]
	s_nop 0
	v_addc_co_u32_e32 v49, vcc, 0, v141, vcc
	v_pk_mul_f32 v[46:47], v[50:51], v[50:51]
	v_add_f32_e32 v46, v46, v47
	v_add_f32_e32 v44, v44, v45
	v_add_f32_e32 v42, v42, v43
	v_add_f32_e32 v40, v40, v41
	v_add_f32_e32 v44, v44, v46
	v_add_f32_e32 v40, v40, v42
	v_add_f32_e32 v40, v40, v44
	s_waitcnt vmcnt(15)
	v_mov_b32_e32 v48, v250
	v_mov_b32_e32 v49, v251
	v_mov_b32_e32 v50, v252
	v_mov_b32_e32 v51, v253
	v_lshlrev_b32_e32 v54, 16, v48
	v_and_b32_e32 v55, 0xffff0000, v48
	v_lshlrev_b32_e32 v48, 16, v49
	v_and_b32_e32 v49, 0xffff0000, v49
	v_pk_add_f32 v[38:39], v[38:39], v[48:49]
	v_lshlrev_b32_e32 v48, 16, v50
	v_and_b32_e32 v49, 0xffff0000, v50
	v_pk_add_f32 v[48:49], v[32:33], v[48:49]
	v_lshlrev_b32_e32 v32, 16, v51
	v_and_b32_e32 v33, 0xffff0000, v51
	v_pk_add_f32 v[36:37], v[36:37], v[54:55]
	v_pk_add_f32 v[50:51], v[34:35], v[32:33]
	v_cvt_pk_bf16_f32 v32, v36, v37
	v_cvt_pk_bf16_f32 v33, v38, v39
	v_cvt_pk_bf16_f32 v34, v48, v49
	v_cvt_pk_bf16_f32 v35, v50, v51
	global_store_dwordx4 v[52:53], v[32:35], off offset:256
	s_nop 1
	v_pk_mul_f32 v[32:33], v[36:37], v[36:37]
	v_pk_mul_f32 v[34:35], v[38:39], v[38:39]
	v_pk_mul_f32 v[36:37], v[48:49], v[48:49]
	v_pk_mul_f32 v[38:39], v[50:51], v[50:51]
	v_add_f32_e32 v36, v36, v37
	v_add_f32_e32 v38, v38, v39
	v_add_f32_e32 v34, v34, v35
	v_add_f32_e32 v32, v32, v33
	v_add_f32_e32 v36, v36, v38
	v_add_f32_e32 v32, v32, v34
	v_add_f32_e32 v32, v32, v36
	v_add_f32_e32 v32, v40, v32
	ds_bpermute_b32 v33, v151, v32
	s_waitcnt lgkmcnt(0)
	v_add_f32_e32 v32, v32, v33
	ds_bpermute_b32 v33, v152, v32
	s_and_saveexec_b64 s[4:5], s[6:7]
	s_cbranch_execz .LBB0_1461
	s_waitcnt lgkmcnt(0)
	v_add_f32_e32 v32, v32, v33
	v_mul_f32_e32 v32, 0x4b800000, v32
	v_trunc_f32_e32 v32, v32
	v_mul_f32_e32 v33, 0x2f800000, v32
	v_floor_f32_e32 v33, v33
	v_fmac_f32_e32 v32, 0xcf800000, v33
	v_cvt_u32_f32_e32 v32, v32
	v_cvt_u32_f32_e32 v33, v33
	global_atomic_add_x2 v[112:113], v[32:33], off offset:1152
;     __device__ __forceinline__ static u32x4 pack8(const f32x4& a, const f32x4& b) { u32x4 w; w.x = cvtpk(a[0], a[1]); w.y = cvtpk(a[2], a[3]); w.z = cvtpk(b[0], b[1]); w.w = cvtpk(b[2], b[3]); return w; }
;     __device__ __forceinline__ static float sumsq8(const f32x4& a, const f32x4& b) { return ((a[0] * a[0] + a[1] * a[1]) + (a[2] * a[2] + a[3] * a[3])) + ((b[0] * b[0] + b[1] * b[1]) + (b[2] * b[2] + b[3] * b[3])); }
;     __device__ __forceinline__ static void row_atomic(sq_t* sq, int row, float s, int lane, int fq) { s += shx(s, lane, 16); s += shx(s, lane, 32); if (fq == 0) (void)__hip_atomic_fetch_add(sq + row, (sq_t)(s * 16777216.f), __ATOMIC_RELAXED, __HIP_MEMORY_SCOPE_AGENT); }
;     __device__ __forceinline__ void operator()(const f32x4 (&acc)[2][2][4][2], const Unit& u, int wr, int wc, int fr, int fq) const {
;     ...
;         } else if (mode == EM_WO || mode == EM_FF2) {
;             const bf16_t* hb = (const bf16_t*)(ws + WS_H); bf16_t* dst = (mode == EM_FF2 && flag) ? (bf16_t*)(ws + WS_MRG) : (bf16_t*)(ws + WS_H);
;             sq_t* sq = mode == EM_WO ? SQMID : (flag ? SQX + 4 * TCH : SQX);
; #pragma unroll
;             for (int ai = 0; ai < 2; ++ai)
; #pragma unroll
;                 for (int m = 0; m < 4; ++m) { const int row = row0 + ai * HALF + m * 16; float ss = 0.f;
; #pragma unroll
;                     for (int bj = 0; bj < 2; ++bj) { const size_t o = (size_t)row * 1024 + pn * 256 + bj * HALF + cw;
;                         const u32x4 xi = *(const u32x4*)(hb + o); f32x4 r0 = acc[ai][bj][m][0], r1 = acc[ai][bj][m][1];
;                         r0[0] += bflo(xi.x); r0[1] += bfhi(xi.x); r0[2] += bflo(xi.y); r0[3] += bfhi(xi.y); r1[0] += bflo(xi.z); r1[1] += bfhi(xi.z); r1[2] += bflo(xi.w); r1[3] += bfhi(xi.w);
;                         *(u32x4*)(dst + o) = pack8(r0, r1); ss += sumsq8(r0, r1); }
;                     row_atomic(sq, row, ss, lane, fq); }
.LBB0_1461:
	s_or_b64 exec, exec, s[4:5]
	s_mov_b64 s[2:3], 0x50000
	v_lshl_add_u64 v[36:37], v[142:143], 0, s[2:3]
	s_waitcnt lgkmcnt(0)
	v_lshl_add_u64 v[32:33], s[28:29], 0, v[36:37]
	v_lshl_add_u64 v[36:37], s[34:35], 0, v[36:37]
	s_mov_b32 s2, 0x50000
	s_waitcnt vmcnt(15)
	v_mov_b32_e32 v32, v192
	v_mov_b32_e32 v33, v193
	v_mov_b32_e32 v34, v194
	v_mov_b32_e32 v35, v195
	v_lshlrev_b32_e32 v38, 16, v32
	v_and_b32_e32 v39, 0xffff0000, v32
	v_lshlrev_b32_e32 v32, 16, v33
	v_and_b32_e32 v33, 0xffff0000, v33
	v_pk_add_f32 v[30:31], v[30:31], v[32:33]
	v_lshlrev_b32_e32 v32, 16, v34
	v_and_b32_e32 v33, 0xffff0000, v34
	v_pk_add_f32 v[32:33], v[24:25], v[32:33]
	v_lshlrev_b32_e32 v24, 16, v35
	v_and_b32_e32 v25, 0xffff0000, v35
	v_pk_add_f32 v[28:29], v[28:29], v[38:39]
	v_pk_add_f32 v[34:35], v[26:27], v[24:25]
	v_cvt_pk_bf16_f32 v24, v28, v29
	v_cvt_pk_bf16_f32 v25, v30, v31
	v_cvt_pk_bf16_f32 v26, v32, v33
	v_cvt_pk_bf16_f32 v27, v34, v35
	global_store_dwordx4 v[36:37], v[24:27], off
	s_nop 1
	v_pk_mul_f32 v[24:25], v[28:29], v[28:29]
	v_pk_mul_f32 v[28:29], v[32:33], v[32:33]
	v_add_co_u32_e32 v32, vcc, s2, v140
	v_pk_mul_f32 v[26:27], v[30:31], v[30:31]
	s_nop 0
	v_addc_co_u32_e32 v33, vcc, 0, v141, vcc
	v_pk_mul_f32 v[30:31], v[34:35], v[34:35]
	v_add_f32_e32 v30, v30, v31
	v_add_f32_e32 v28, v28, v29
	v_add_f32_e32 v26, v26, v27
	v_add_f32_e32 v24, v24, v25
	v_add_f32_e32 v28, v28, v30
	v_add_f32_e32 v24, v24, v26
	v_add_f32_e32 v24, v24, v28
	s_waitcnt vmcnt(14)
	v_mov_b32_e32 v32, v196
	v_mov_b32_e32 v33, v197
	v_mov_b32_e32 v34, v198
	v_mov_b32_e32 v35, v199
	v_lshlrev_b32_e32 v38, 16, v32
	v_and_b32_e32 v39, 0xffff0000, v32
	v_lshlrev_b32_e32 v32, 16, v33
	v_and_b32_e32 v33, 0xffff0000, v33
	v_pk_add_f32 v[22:23], v[22:23], v[32:33]
	v_lshlrev_b32_e32 v32, 16, v34
	v_and_b32_e32 v33, 0xffff0000, v34
	v_pk_add_f32 v[32:33], v[16:17], v[32:33]
	v_lshlrev_b32_e32 v16, 16, v35
	v_and_b32_e32 v17, 0xffff0000, v35
	v_pk_add_f32 v[20:21], v[20:21], v[38:39]
	v_pk_add_f32 v[34:35], v[18:19], v[16:17]
	v_cvt_pk_bf16_f32 v16, v20, v21
	v_cvt_pk_bf16_f32 v17, v22, v23
	v_cvt_pk_bf16_f32 v18, v32, v33
	v_cvt_pk_bf16_f32 v19, v34, v35
	global_store_dwordx4 v[36:37], v[16:19], off offset:256
	s_nop 1
	v_pk_mul_f32 v[16:17], v[20:21], v[20:21]
	v_pk_mul_f32 v[18:19], v[22:23], v[22:23]
	v_pk_mul_f32 v[20:21], v[32:33], v[32:33]
	v_pk_mul_f32 v[22:23], v[34:35], v[34:35]
	v_add_f32_e32 v20, v20, v21
	v_add_f32_e32 v22, v22, v23
	v_add_f32_e32 v18, v18, v19
	v_add_f32_e32 v16, v16, v17
	v_add_f32_e32 v20, v20, v22
	v_add_f32_e32 v16, v16, v18
	v_add_f32_e32 v16, v16, v20
	v_add_f32_e32 v16, v24, v16
	ds_bpermute_b32 v17, v151, v16
	s_waitcnt lgkmcnt(0)
	v_add_f32_e32 v16, v16, v17
	ds_bpermute_b32 v17, v152, v16
	s_and_saveexec_b64 s[4:5], s[6:7]
	s_cbranch_execz .LBB0_1463
	s_waitcnt lgkmcnt(0)
	v_add_f32_e32 v16, v16, v17
	v_mul_f32_e32 v16, 0x4b800000, v16
	v_trunc_f32_e32 v16, v16
	v_mul_f32_e32 v17, 0x2f800000, v16
	v_floor_f32_e32 v17, v17
	v_fmac_f32_e32 v16, 0xcf800000, v17
	v_cvt_u32_f32_e32 v16, v16
	v_cvt_u32_f32_e32 v17, v17
	global_atomic_add_x2 v[112:113], v[16:17], off offset:1280
.LBB0_1463:
	s_or_b64 exec, exec, s[4:5]
	s_mov_b64 s[2:3], 0x58000
	v_lshl_add_u64 v[20:21], v[142:143], 0, s[2:3]
	s_waitcnt lgkmcnt(0)
	v_lshl_add_u64 v[16:17], s[28:29], 0, v[20:21]
	v_lshl_add_u64 v[20:21], s[34:35], 0, v[20:21]
	s_mov_b32 s2, 0x58000
	s_waitcnt vmcnt(13)
	v_mov_b32_e32 v16, v200
	v_mov_b32_e32 v17, v201
	v_mov_b32_e32 v18, v202
	v_mov_b32_e32 v19, v203
	v_lshlrev_b32_e32 v22, 16, v16
	v_and_b32_e32 v23, 0xffff0000, v16
	v_lshlrev_b32_e32 v16, 16, v17
	v_and_b32_e32 v17, 0xffff0000, v17
	v_pk_add_f32 v[14:15], v[14:15], v[16:17]
	v_lshlrev_b32_e32 v16, 16, v18
	v_and_b32_e32 v17, 0xffff0000, v18
	v_pk_add_f32 v[16:17], v[8:9], v[16:17]
	v_lshlrev_b32_e32 v8, 16, v19
	v_and_b32_e32 v9, 0xffff0000, v19
	v_pk_add_f32 v[12:13], v[12:13], v[22:23]
	v_pk_add_f32 v[18:19], v[10:11], v[8:9]
	v_cvt_pk_bf16_f32 v8, v12, v13
	v_cvt_pk_bf16_f32 v9, v14, v15
	v_cvt_pk_bf16_f32 v10, v16, v17
	v_cvt_pk_bf16_f32 v11, v18, v19
	global_store_dwordx4 v[20:21], v[8:11], off
	s_nop 1
	v_pk_mul_f32 v[8:9], v[12:13], v[12:13]
	v_pk_mul_f32 v[12:13], v[16:17], v[16:17]
	v_add_co_u32_e32 v16, vcc, s2, v140
	v_pk_mul_f32 v[10:11], v[14:15], v[14:15]
	s_nop 0
	v_addc_co_u32_e32 v17, vcc, 0, v141, vcc
	v_pk_mul_f32 v[14:15], v[18:19], v[18:19]
	v_add_f32_e32 v14, v14, v15
	v_add_f32_e32 v12, v12, v13
	v_add_f32_e32 v10, v10, v11
	v_add_f32_e32 v8, v8, v9
	v_add_f32_e32 v12, v12, v14
	v_add_f32_e32 v8, v8, v10
	v_add_f32_e32 v8, v8, v12
	s_waitcnt vmcnt(12)
	v_mov_b32_e32 v16, v216
	v_mov_b32_e32 v17, v217
	v_mov_b32_e32 v18, v218
	v_mov_b32_e32 v19, v219
	v_lshlrev_b32_e32 v22, 16, v16
	v_and_b32_e32 v23, 0xffff0000, v16
	v_lshlrev_b32_e32 v16, 16, v17
	v_and_b32_e32 v17, 0xffff0000, v17
	v_pk_add_f32 v[6:7], v[6:7], v[16:17]
	v_lshlrev_b32_e32 v16, 16, v18
	v_and_b32_e32 v17, 0xffff0000, v18
	v_pk_add_f32 v[16:17], v[0:1], v[16:17]
	v_lshlrev_b32_e32 v0, 16, v19
	v_and_b32_e32 v1, 0xffff0000, v19
	v_pk_add_f32 v[4:5], v[4:5], v[22:23]
	v_pk_add_f32 v[18:19], v[2:3], v[0:1]
	v_cvt_pk_bf16_f32 v0, v4, v5
	v_cvt_pk_bf16_f32 v1, v6, v7
	v_cvt_pk_bf16_f32 v2, v16, v17
	v_cvt_pk_bf16_f32 v3, v18, v19
	global_store_dwordx4 v[20:21], v[0:3], off offset:256
	s_nop 1
	v_pk_mul_f32 v[0:1], v[4:5], v[4:5]
	v_pk_mul_f32 v[2:3], v[6:7], v[6:7]
	v_pk_mul_f32 v[4:5], v[16:17], v[16:17]
	v_pk_mul_f32 v[6:7], v[18:19], v[18:19]
	v_add_f32_e32 v4, v4, v5
	v_add_f32_e32 v6, v6, v7
	v_add_f32_e32 v2, v2, v3
	v_add_f32_e32 v0, v0, v1
	v_add_f32_e32 v4, v4, v6
	v_add_f32_e32 v0, v0, v2
	v_add_f32_e32 v0, v0, v4
	v_add_f32_e32 v0, v8, v0
	ds_bpermute_b32 v1, v151, v0
	s_waitcnt lgkmcnt(0)
	v_add_f32_e32 v0, v0, v1
	ds_bpermute_b32 v1, v152, v0
	s_and_saveexec_b64 s[4:5], s[6:7]
	s_cbranch_execz .LBB0_1465
	s_waitcnt lgkmcnt(0)
	v_add_f32_e32 v0, v0, v1
	v_mul_f32_e32 v0, 0x4b800000, v0
	v_trunc_f32_e32 v0, v0
	v_mul_f32_e32 v1, 0x2f800000, v0
	v_floor_f32_e32 v1, v1
	v_fmac_f32_e32 v0, 0xcf800000, v1
	v_cvt_u32_f32_e32 v0, v0
	v_cvt_u32_f32_e32 v1, v1
	global_atomic_add_x2 v[112:113], v[0:1], off offset:1408
